# static priority raise (s_setprio 2) for the attention compute blocks in the mixer so the matrix-bound wave issues ahead of the streaming wave on its SIMD
# speedup vs baseline: 1.0018x; 1.0018x over previous
.Latt_compute:
	s_setprio 2
	ds_read_b128 v[48:51], v72 offset:0
	ds_read_b128 v[52:55], v146 offset:0
	ds_read_b128 v[56:59], v72 offset:2048
	ds_read_b128 v[60:63], v146 offset:2048
	ds_read_b128 v[64:67], v72 offset:4096
	ds_read_b128 v[68:71], v146 offset:4096
	ds_read_b128 v[32:35], v72 offset:6144
	ds_read_b128 v[36:39], v146 offset:6144
	ds_read_b128 v[40:43], v72 offset:8192
	s_waitcnt lgkmcnt(8)
	v_mfma_f32_16x16x32_bf16 v[78:81], v[48:51], v[0:3], 0
	ds_read_b128 v[44:47], v146 offset:8192
	s_waitcnt lgkmcnt(8)
	v_mfma_f32_16x16x32_bf16 v[78:81], v[52:55], v[4:7], v[78:81]
	ds_read_b128 v[48:51], v72 offset:10240
	s_waitcnt lgkmcnt(8)
	v_mfma_f32_16x16x32_bf16 v[82:85], v[56:59], v[0:3], 0
	ds_read_b128 v[52:55], v146 offset:10240
	s_waitcnt lgkmcnt(8)
	v_mfma_f32_16x16x32_bf16 v[82:85], v[60:63], v[4:7], v[82:85]
	ds_read_b128 v[56:59], v72 offset:12288
	s_waitcnt lgkmcnt(8)
	v_mfma_f32_16x16x32_bf16 v[86:89], v[64:67], v[0:3], 0
	ds_read_b128 v[60:63], v146 offset:12288
	s_waitcnt lgkmcnt(8)
	v_mfma_f32_16x16x32_bf16 v[86:89], v[68:71], v[4:7], v[86:89]
	ds_read_b128 v[64:67], v72 offset:14336
	s_waitcnt lgkmcnt(8)
	v_mfma_f32_16x16x32_bf16 v[90:93], v[32:35], v[0:3], 0
	ds_read_b128 v[68:71], v146 offset:14336
	s_waitcnt lgkmcnt(8)
	v_mfma_f32_16x16x32_bf16 v[90:93], v[36:39], v[4:7], v[90:93]
	ds_read_b128 v[32:35], v72 offset:16384
	s_waitcnt lgkmcnt(8)
	v_mfma_f32_16x16x32_bf16 v[94:97], v[40:43], v[0:3], 0
	ds_read_b128 v[36:39], v146 offset:16384
	s_waitcnt lgkmcnt(8)
	v_mfma_f32_16x16x32_bf16 v[94:97], v[44:47], v[4:7], v[94:97]
	ds_read_b128 v[40:43], v72 offset:18432
	s_waitcnt lgkmcnt(8)
	v_mfma_f32_16x16x32_bf16 v[98:101], v[48:51], v[0:3], 0
	ds_read_b128 v[44:47], v146 offset:18432
	s_waitcnt lgkmcnt(8)
	v_mfma_f32_16x16x32_bf16 v[98:101], v[52:55], v[4:7], v[98:101]
	ds_read_b128 v[48:51], v72 offset:20480
	s_waitcnt lgkmcnt(8)
	v_mfma_f32_16x16x32_bf16 v[102:105], v[56:59], v[0:3], 0
	ds_read_b128 v[52:55], v146 offset:20480
	s_waitcnt lgkmcnt(8)
	v_mfma_f32_16x16x32_bf16 v[102:105], v[60:63], v[4:7], v[102:105]
	ds_read_b128 v[56:59], v72 offset:22528
	s_waitcnt lgkmcnt(8)
	v_mfma_f32_16x16x32_bf16 v[106:109], v[64:67], v[0:3], 0
	ds_read_b128 v[60:63], v146 offset:22528
	s_waitcnt lgkmcnt(8)
	v_mfma_f32_16x16x32_bf16 v[106:109], v[68:71], v[4:7], v[106:109]
	ds_read_b128 v[64:67], v72 offset:24576
	s_waitcnt lgkmcnt(8)
	v_mfma_f32_16x16x32_bf16 v[110:113], v[32:35], v[0:3], 0
	ds_read_b128 v[68:71], v146 offset:24576
	s_waitcnt lgkmcnt(8)
	v_mfma_f32_16x16x32_bf16 v[110:113], v[36:39], v[4:7], v[110:113]
	ds_read_b128 v[32:35], v72 offset:26624
	s_waitcnt lgkmcnt(8)
	v_mfma_f32_16x16x32_bf16 v[114:117], v[40:43], v[0:3], 0
	ds_read_b128 v[36:39], v146 offset:26624
	s_waitcnt lgkmcnt(8)
	v_mfma_f32_16x16x32_bf16 v[114:117], v[44:47], v[4:7], v[114:117]
	ds_read_b128 v[40:43], v72 offset:28672
	s_waitcnt lgkmcnt(8)
	v_mfma_f32_16x16x32_bf16 v[118:121], v[48:51], v[0:3], 0
	ds_read_b128 v[44:47], v146 offset:28672
	s_waitcnt lgkmcnt(8)
	v_mfma_f32_16x16x32_bf16 v[118:121], v[52:55], v[4:7], v[118:121]
	ds_read_b128 v[48:51], v72 offset:30720
	s_waitcnt lgkmcnt(8)
	v_mfma_f32_16x16x32_bf16 v[122:125], v[56:59], v[0:3], 0
	ds_read_b128 v[52:55], v146 offset:30720
	s_waitcnt lgkmcnt(8)
	v_mfma_f32_16x16x32_bf16 v[122:125], v[60:63], v[4:7], v[122:125]
	s_waitcnt lgkmcnt(7)
	v_mfma_f32_16x16x32_bf16 v[126:129], v[64:67], v[0:3], 0
	s_waitcnt lgkmcnt(6)
	v_mfma_f32_16x16x32_bf16 v[126:129], v[68:71], v[4:7], v[126:129]
	s_waitcnt lgkmcnt(5)
	v_mfma_f32_16x16x32_bf16 v[130:133], v[32:35], v[0:3], 0
	s_waitcnt lgkmcnt(4)
	v_mfma_f32_16x16x32_bf16 v[130:133], v[36:39], v[4:7], v[130:133]
	s_waitcnt lgkmcnt(3)
	v_mfma_f32_16x16x32_bf16 v[134:137], v[40:43], v[0:3], 0
	s_waitcnt lgkmcnt(2)
	v_mfma_f32_16x16x32_bf16 v[134:137], v[44:47], v[4:7], v[134:137]
	s_waitcnt lgkmcnt(1)
	v_mfma_f32_16x16x32_bf16 v[138:141], v[48:51], v[0:3], 0
	s_waitcnt lgkmcnt(0)
	v_mfma_f32_16x16x32_bf16 v[138:141], v[52:55], v[4:7], v[138:141]
	ds_read_b64 v[48:49], v73 offset:36864
	ds_read_b64 v[50:51], v73 offset:36896
	ds_read_b64 v[52:53], v73 offset:45312
	ds_read_b64 v[54:55], v73 offset:45344
	ds_read_b64 v[56:57], v73 offset:53760
	ds_read_b64 v[58:59], v73 offset:53792
	ds_read_b64 v[60:61], v73 offset:62208
	ds_read_b64 v[62:63], v73 offset:62240
	ds_read_b64 v[64:65], v73 offset:36928
	ds_read_b64 v[66:67], v73 offset:36960
	ds_read_b64 v[68:69], v73 offset:45376
	ds_read_b64 v[70:71], v73 offset:45408
	v_max3_f32 v36, v78, v79, v80
	v_max3_f32 v36, v36, v81, v82
	v_max3_f32 v36, v36, v83, v84
	v_max3_f32 v36, v36, v85, v86
	v_max3_f32 v36, v36, v87, v88
	v_max3_f32 v36, v36, v89, v90
	v_max3_f32 v36, v36, v91, v92
	v_max3_f32 v36, v36, v93, v94
	v_max3_f32 v36, v36, v95, v96
	v_max3_f32 v36, v36, v97, v98
	v_max3_f32 v36, v36, v99, v100
	v_max3_f32 v36, v36, v101, v102
	v_max3_f32 v36, v36, v103, v104
	v_max3_f32 v36, v36, v105, v106
	v_max3_f32 v36, v36, v107, v108
	v_max3_f32 v36, v36, v109, v110
	v_max3_f32 v36, v36, v111, v112
	v_max3_f32 v36, v36, v113, v114
	v_max3_f32 v36, v36, v115, v116
	v_max3_f32 v36, v36, v117, v118
	v_max3_f32 v36, v36, v119, v120
	v_max3_f32 v36, v36, v121, v122
	v_max3_f32 v36, v36, v123, v124
	v_max3_f32 v36, v36, v125, v126
	v_max3_f32 v36, v36, v127, v128
	v_max3_f32 v36, v36, v129, v130
	v_max3_f32 v36, v36, v131, v132
	v_max3_f32 v36, v36, v133, v134
	v_max3_f32 v36, v36, v135, v136
	v_max3_f32 v36, v36, v137, v138
	v_max3_f32 v36, v36, v139, v140
	v_max_f32_e32 v36, v36, v141
	v_mov_b32_e32 v37, v36
	s_nop 1
	v_permlane16_swap_b32_e32 v36, v37
	v_max_f32_e32 v36, v36, v37
	v_mov_b32_e32 v37, v36
	s_nop 1
	v_permlane32_swap_b32_e32 v36, v37
	v_max_f32_e32 v36, v36, v37
	v_mul_f32_e64 v38, v36, -v144
	v_mov_b32_e32 v40, 0
	v_mov_b32_e32 v41, 0
	v_mov_b32_e32 v39, v38
	v_pk_fma_f32 v[78:79], v[78:79], v[144:145], v[38:39]
	v_pk_fma_f32 v[80:81], v[80:81], v[144:145], v[38:39]
	v_exp_f32_e32 v78, v78
	v_exp_f32_e32 v79, v79
	v_exp_f32_e32 v80, v80
	v_exp_f32_e32 v81, v81
	v_pk_fma_f32 v[82:83], v[82:83], v[144:145], v[38:39]
	v_pk_fma_f32 v[84:85], v[84:85], v[144:145], v[38:39]
	v_exp_f32_e32 v82, v82
	v_exp_f32_e32 v83, v83
	v_exp_f32_e32 v84, v84
	v_exp_f32_e32 v85, v85
	v_pk_add_f32 v[40:41], v[40:41], v[78:79]
	v_pk_add_f32 v[40:41], v[40:41], v[80:81]
	v_pk_fma_f32 v[86:87], v[86:87], v[144:145], v[38:39]
	v_pk_fma_f32 v[88:89], v[88:89], v[144:145], v[38:39]
	v_exp_f32_e32 v86, v86
	v_exp_f32_e32 v87, v87
	v_exp_f32_e32 v88, v88
	v_exp_f32_e32 v89, v89
	v_pk_add_f32 v[40:41], v[40:41], v[82:83]
	v_pk_add_f32 v[40:41], v[40:41], v[84:85]
	v_pk_fma_f32 v[90:91], v[90:91], v[144:145], v[38:39]
	v_pk_fma_f32 v[92:93], v[92:93], v[144:145], v[38:39]
	v_exp_f32_e32 v90, v90
	v_exp_f32_e32 v91, v91
	v_exp_f32_e32 v92, v92
	v_exp_f32_e32 v93, v93
	v_pk_add_f32 v[40:41], v[40:41], v[86:87]
	v_pk_add_f32 v[40:41], v[40:41], v[88:89]
	v_pk_fma_f32 v[94:95], v[94:95], v[144:145], v[38:39]
	v_pk_fma_f32 v[96:97], v[96:97], v[144:145], v[38:39]
	v_exp_f32_e32 v94, v94
	v_exp_f32_e32 v95, v95
	v_exp_f32_e32 v96, v96
	v_exp_f32_e32 v97, v97
	v_pk_add_f32 v[40:41], v[40:41], v[90:91]
	v_pk_add_f32 v[40:41], v[40:41], v[92:93]
	v_pk_fma_f32 v[98:99], v[98:99], v[144:145], v[38:39]
	v_pk_fma_f32 v[100:101], v[100:101], v[144:145], v[38:39]
	v_exp_f32_e32 v98, v98
	v_exp_f32_e32 v99, v99
	v_exp_f32_e32 v100, v100
	v_exp_f32_e32 v101, v101
	v_pk_add_f32 v[40:41], v[40:41], v[94:95]
	v_pk_add_f32 v[40:41], v[40:41], v[96:97]
	v_pk_fma_f32 v[102:103], v[102:103], v[144:145], v[38:39]
	v_pk_fma_f32 v[104:105], v[104:105], v[144:145], v[38:39]
	v_exp_f32_e32 v102, v102
	v_exp_f32_e32 v103, v103
	v_exp_f32_e32 v104, v104
	v_exp_f32_e32 v105, v105
	v_pk_add_f32 v[40:41], v[40:41], v[98:99]
	v_pk_add_f32 v[40:41], v[40:41], v[100:101]
	v_pk_fma_f32 v[106:107], v[106:107], v[144:145], v[38:39]
	v_pk_fma_f32 v[108:109], v[108:109], v[144:145], v[38:39]
	v_exp_f32_e32 v106, v106
	v_exp_f32_e32 v107, v107
	v_exp_f32_e32 v108, v108
	v_exp_f32_e32 v109, v109
	v_pk_add_f32 v[40:41], v[40:41], v[102:103]
	v_pk_add_f32 v[40:41], v[40:41], v[104:105]
	v_pk_fma_f32 v[110:111], v[110:111], v[144:145], v[38:39]
	v_pk_fma_f32 v[112:113], v[112:113], v[144:145], v[38:39]
	v_exp_f32_e32 v110, v110
	v_exp_f32_e32 v111, v111
	v_exp_f32_e32 v112, v112
	v_exp_f32_e32 v113, v113
	v_pk_add_f32 v[40:41], v[40:41], v[106:107]
	v_pk_add_f32 v[40:41], v[40:41], v[108:109]
	v_pk_fma_f32 v[114:115], v[114:115], v[144:145], v[38:39]
	v_pk_fma_f32 v[116:117], v[116:117], v[144:145], v[38:39]
	v_exp_f32_e32 v114, v114
	v_exp_f32_e32 v115, v115
	v_exp_f32_e32 v116, v116
	v_exp_f32_e32 v117, v117
	v_pk_add_f32 v[40:41], v[40:41], v[110:111]
	v_pk_add_f32 v[40:41], v[40:41], v[112:113]
	v_pk_fma_f32 v[118:119], v[118:119], v[144:145], v[38:39]
	v_pk_fma_f32 v[120:121], v[120:121], v[144:145], v[38:39]
	v_exp_f32_e32 v118, v118
	v_exp_f32_e32 v119, v119
	v_exp_f32_e32 v120, v120
	v_exp_f32_e32 v121, v121
	v_pk_add_f32 v[40:41], v[40:41], v[114:115]
	v_pk_add_f32 v[40:41], v[40:41], v[116:117]
	v_pk_fma_f32 v[122:123], v[122:123], v[144:145], v[38:39]
	v_pk_fma_f32 v[124:125], v[124:125], v[144:145], v[38:39]
	v_exp_f32_e32 v122, v122
	v_exp_f32_e32 v123, v123
	v_exp_f32_e32 v124, v124
	v_exp_f32_e32 v125, v125
	v_pk_add_f32 v[40:41], v[40:41], v[118:119]
	v_pk_add_f32 v[40:41], v[40:41], v[120:121]
	v_pk_fma_f32 v[126:127], v[126:127], v[144:145], v[38:39]
	v_pk_fma_f32 v[128:129], v[128:129], v[144:145], v[38:39]
	v_exp_f32_e32 v126, v126
	v_exp_f32_e32 v127, v127
	v_exp_f32_e32 v128, v128
	v_exp_f32_e32 v129, v129
	v_pk_add_f32 v[40:41], v[40:41], v[122:123]
	v_pk_add_f32 v[40:41], v[40:41], v[124:125]
	v_pk_fma_f32 v[130:131], v[130:131], v[144:145], v[38:39]
	v_pk_fma_f32 v[132:133], v[132:133], v[144:145], v[38:39]
	v_exp_f32_e32 v130, v130
	v_exp_f32_e32 v131, v131
	v_exp_f32_e32 v132, v132
	v_exp_f32_e32 v133, v133
	v_pk_add_f32 v[40:41], v[40:41], v[126:127]
	v_pk_add_f32 v[40:41], v[40:41], v[128:129]
	v_pk_fma_f32 v[134:135], v[134:135], v[144:145], v[38:39]
	v_pk_fma_f32 v[136:137], v[136:137], v[144:145], v[38:39]
	v_exp_f32_e32 v134, v134
	v_exp_f32_e32 v135, v135
	v_exp_f32_e32 v136, v136
	v_exp_f32_e32 v137, v137
	v_pk_add_f32 v[40:41], v[40:41], v[130:131]
	v_pk_add_f32 v[40:41], v[40:41], v[132:133]
	v_pk_fma_f32 v[138:139], v[138:139], v[144:145], v[38:39]
	v_pk_fma_f32 v[140:141], v[140:141], v[144:145], v[38:39]
	v_exp_f32_e32 v138, v138
	v_exp_f32_e32 v139, v139
	v_exp_f32_e32 v140, v140
	v_exp_f32_e32 v141, v141
	v_pk_add_f32 v[40:41], v[40:41], v[134:135]
	v_pk_add_f32 v[40:41], v[40:41], v[136:137]
	s_nop 0
	v_pk_add_f32 v[40:41], v[40:41], v[138:139]
	v_pk_add_f32 v[40:41], v[40:41], v[140:141]
	v_add_f32_e32 v36, v40, v41
	v_mov_b32_e32 v37, v36
	s_nop 1
	v_permlane16_swap_b32_e32 v36, v37
	v_add_f32_e32 v36, v36, v37
	v_mov_b32_e32 v37, v36
	s_nop 1
	v_permlane32_swap_b32_e32 v36, v37
	v_add_f32_e32 v36, v36, v37
	v_rcp_f32_e32 v142, v36
	v_cvt_pk_bf16_f32 v78, v78, v79
	v_cvt_pk_bf16_f32 v79, v80, v81
	v_cvt_pk_bf16_f32 v80, v82, v83
	v_cvt_pk_bf16_f32 v81, v84, v85
	v_cvt_pk_bf16_f32 v86, v86, v87
	v_cvt_pk_bf16_f32 v87, v88, v89
	v_cvt_pk_bf16_f32 v88, v90, v91
	v_cvt_pk_bf16_f32 v89, v92, v93
	v_cvt_pk_bf16_f32 v94, v94, v95
	v_cvt_pk_bf16_f32 v95, v96, v97
	v_cvt_pk_bf16_f32 v96, v98, v99
	v_cvt_pk_bf16_f32 v97, v100, v101
	v_cvt_pk_bf16_f32 v102, v102, v103
	v_cvt_pk_bf16_f32 v103, v104, v105
	v_cvt_pk_bf16_f32 v104, v106, v107
	v_cvt_pk_bf16_f32 v105, v108, v109
	v_cvt_pk_bf16_f32 v110, v110, v111
	v_cvt_pk_bf16_f32 v111, v112, v113
	v_cvt_pk_bf16_f32 v112, v114, v115
	v_cvt_pk_bf16_f32 v113, v116, v117
	v_cvt_pk_bf16_f32 v118, v118, v119
	v_cvt_pk_bf16_f32 v119, v120, v121
	v_cvt_pk_bf16_f32 v120, v122, v123
	v_cvt_pk_bf16_f32 v121, v124, v125
	v_cvt_pk_bf16_f32 v126, v126, v127
	v_cvt_pk_bf16_f32 v127, v128, v129
	v_cvt_pk_bf16_f32 v128, v130, v131
	v_cvt_pk_bf16_f32 v129, v132, v133
	v_cvt_pk_bf16_f32 v134, v134, v135
	v_cvt_pk_bf16_f32 v135, v136, v137
	v_cvt_pk_bf16_f32 v136, v138, v139
	v_cvt_pk_bf16_f32 v137, v140, v141
	v_fma_f32 v143, -v36, v142, 1.0
	v_fma_f32 v142, v143, v142, v142
	v_mov_b32_e32 v143, v142
	ds_read_b64 v[82:83], v73 offset:53824
	ds_read_b64 v[84:85], v73 offset:53856
	s_waitcnt lgkmcnt(12)
	v_mfma_f32_16x16x32_bf16 v[32:35], v[48:51], v[78:81], 0
	ds_read_b64 v[90:91], v73 offset:62272
	ds_read_b64 v[92:93], v73 offset:62304
	s_waitcnt lgkmcnt(12)
	v_mfma_f32_16x16x32_bf16 v[36:39], v[52:55], v[78:81], 0
	ds_read_b64 v[48:49], v73 offset:36992
	ds_read_b64 v[50:51], v73 offset:37024
	s_waitcnt lgkmcnt(12)
	v_mfma_f32_16x16x32_bf16 v[40:43], v[56:59], v[78:81], 0
	ds_read_b64 v[52:53], v73 offset:45440
	ds_read_b64 v[54:55], v73 offset:45472
	s_waitcnt lgkmcnt(12)
	v_mfma_f32_16x16x32_bf16 v[44:47], v[60:63], v[78:81], 0
	ds_read_b64 v[56:57], v73 offset:53888
	ds_read_b64 v[58:59], v73 offset:53920
	s_waitcnt lgkmcnt(12)
	v_mfma_f32_16x16x32_bf16 v[32:35], v[64:67], v[86:89], v[32:35]
	ds_read_b64 v[60:61], v73 offset:62336
	ds_read_b64 v[62:63], v73 offset:62368
	s_waitcnt lgkmcnt(12)
	v_mfma_f32_16x16x32_bf16 v[36:39], v[68:71], v[86:89], v[36:39]
	ds_read_b64 v[64:65], v73 offset:37056
	ds_read_b64 v[66:67], v73 offset:37088
	s_waitcnt lgkmcnt(12)
	v_mfma_f32_16x16x32_bf16 v[40:43], v[82:85], v[86:89], v[40:43]
	ds_read_b64 v[68:69], v73 offset:45504
	ds_read_b64 v[70:71], v73 offset:45536
	s_waitcnt lgkmcnt(12)
	v_mfma_f32_16x16x32_bf16 v[44:47], v[90:93], v[86:89], v[44:47]
	ds_read_b64 v[82:83], v73 offset:53952
	ds_read_b64 v[84:85], v73 offset:53984
	s_waitcnt lgkmcnt(12)
	v_mfma_f32_16x16x32_bf16 v[32:35], v[48:51], v[94:97], v[32:35]
	ds_read_b64 v[90:91], v73 offset:62400
	ds_read_b64 v[92:93], v73 offset:62432
	s_waitcnt lgkmcnt(12)
	v_mfma_f32_16x16x32_bf16 v[36:39], v[52:55], v[94:97], v[36:39]
	ds_read_b64 v[48:49], v73 offset:37120
	ds_read_b64 v[50:51], v73 offset:37152
	s_waitcnt lgkmcnt(12)
	v_mfma_f32_16x16x32_bf16 v[40:43], v[56:59], v[94:97], v[40:43]
	ds_read_b64 v[52:53], v73 offset:45568
	ds_read_b64 v[54:55], v73 offset:45600
	s_waitcnt lgkmcnt(12)
	v_mfma_f32_16x16x32_bf16 v[44:47], v[60:63], v[94:97], v[44:47]
	ds_read_b64 v[56:57], v73 offset:54016
	ds_read_b64 v[58:59], v73 offset:54048
	s_waitcnt lgkmcnt(12)
	v_mfma_f32_16x16x32_bf16 v[32:35], v[64:67], v[102:105], v[32:35]
	ds_read_b64 v[60:61], v73 offset:62464
	ds_read_b64 v[62:63], v73 offset:62496
	s_waitcnt lgkmcnt(12)
	v_mfma_f32_16x16x32_bf16 v[36:39], v[68:71], v[102:105], v[36:39]
	ds_read_b64 v[64:65], v73 offset:37184
	ds_read_b64 v[66:67], v73 offset:37216
	s_waitcnt lgkmcnt(12)
	v_mfma_f32_16x16x32_bf16 v[40:43], v[82:85], v[102:105], v[40:43]
	ds_read_b64 v[68:69], v73 offset:45632
	ds_read_b64 v[70:71], v73 offset:45664
	s_waitcnt lgkmcnt(12)
	v_mfma_f32_16x16x32_bf16 v[44:47], v[90:93], v[102:105], v[44:47]
	ds_read_b64 v[82:83], v73 offset:54080
	ds_read_b64 v[84:85], v73 offset:54112
	s_waitcnt lgkmcnt(12)
	v_mfma_f32_16x16x32_bf16 v[32:35], v[48:51], v[110:113], v[32:35]
	ds_read_b64 v[90:91], v73 offset:62528
	ds_read_b64 v[92:93], v73 offset:62560
	s_waitcnt lgkmcnt(12)
	v_mfma_f32_16x16x32_bf16 v[36:39], v[52:55], v[110:113], v[36:39]
	ds_read_b64 v[48:49], v73 offset:37248
	ds_read_b64 v[50:51], v73 offset:37280
	s_waitcnt lgkmcnt(12)
	v_mfma_f32_16x16x32_bf16 v[40:43], v[56:59], v[110:113], v[40:43]
	ds_read_b64 v[52:53], v73 offset:45696
	ds_read_b64 v[54:55], v73 offset:45728
	s_waitcnt lgkmcnt(12)
	v_mfma_f32_16x16x32_bf16 v[44:47], v[60:63], v[110:113], v[44:47]
	ds_read_b64 v[56:57], v73 offset:54144
	ds_read_b64 v[58:59], v73 offset:54176
	s_waitcnt lgkmcnt(12)
	v_mfma_f32_16x16x32_bf16 v[32:35], v[64:67], v[118:121], v[32:35]
	ds_read_b64 v[60:61], v73 offset:62592
	ds_read_b64 v[62:63], v73 offset:62624
	s_waitcnt lgkmcnt(12)
	v_mfma_f32_16x16x32_bf16 v[36:39], v[68:71], v[118:121], v[36:39]
	ds_read_b64 v[64:65], v73 offset:37312
	ds_read_b64 v[66:67], v73 offset:37344
	s_waitcnt lgkmcnt(12)
	v_mfma_f32_16x16x32_bf16 v[40:43], v[82:85], v[118:121], v[40:43]
	ds_read_b64 v[68:69], v73 offset:45760
	ds_read_b64 v[70:71], v73 offset:45792
	s_waitcnt lgkmcnt(12)
	v_mfma_f32_16x16x32_bf16 v[44:47], v[90:93], v[118:121], v[44:47]
	ds_read_b64 v[82:83], v73 offset:54208
	ds_read_b64 v[84:85], v73 offset:54240
	s_waitcnt lgkmcnt(12)
	v_mfma_f32_16x16x32_bf16 v[32:35], v[48:51], v[126:129], v[32:35]
	ds_read_b64 v[90:91], v73 offset:62656
	ds_read_b64 v[92:93], v73 offset:62688
	s_waitcnt lgkmcnt(12)
	v_mfma_f32_16x16x32_bf16 v[36:39], v[52:55], v[126:129], v[36:39]
	s_waitcnt lgkmcnt(10)
	v_mfma_f32_16x16x32_bf16 v[40:43], v[56:59], v[126:129], v[40:43]
	s_waitcnt lgkmcnt(8)
	v_mfma_f32_16x16x32_bf16 v[44:47], v[60:63], v[126:129], v[44:47]
	s_waitcnt lgkmcnt(6)
	v_mfma_f32_16x16x32_bf16 v[32:35], v[64:67], v[134:137], v[32:35]
	s_waitcnt lgkmcnt(4)
	v_mfma_f32_16x16x32_bf16 v[36:39], v[68:71], v[134:137], v[36:39]
	s_waitcnt lgkmcnt(2)
	v_mfma_f32_16x16x32_bf16 v[40:43], v[82:85], v[134:137], v[40:43]
	s_waitcnt lgkmcnt(0)
	v_mfma_f32_16x16x32_bf16 v[44:47], v[90:93], v[134:137], v[44:47]
	ds_read_b128 v[48:51], v72 offset:0
	ds_read_b128 v[52:55], v146 offset:0
	ds_read_b128 v[56:59], v72 offset:2048
	ds_read_b128 v[60:63], v146 offset:2048
	ds_read_b128 v[64:67], v72 offset:4096
	ds_read_b128 v[68:71], v146 offset:4096
	s_add_u32 s16, s12, 0x0
	s_addc_u32 s17, s13, 0
	s_nop 7
	v_pk_mul_f32 v[32:33], v[32:33], v[142:143]
	v_pk_mul_f32 v[34:35], v[34:35], v[142:143]
	v_pk_mul_f32 v[36:37], v[36:37], v[142:143]
	v_pk_mul_f32 v[38:39], v[38:39], v[142:143]
	v_pk_mul_f32 v[40:41], v[40:41], v[142:143]
	v_pk_mul_f32 v[42:43], v[42:43], v[142:143]
	v_pk_mul_f32 v[44:45], v[44:45], v[142:143]
	v_pk_mul_f32 v[46:47], v[46:47], v[142:143]
	v_cvt_pk_bf16_f32 v32, v32, v33
	v_cvt_pk_bf16_f32 v33, v34, v35
	v_cvt_pk_bf16_f32 v36, v36, v37
	v_cvt_pk_bf16_f32 v37, v38, v39
	v_cvt_pk_bf16_f32 v40, v40, v41
	v_cvt_pk_bf16_f32 v41, v42, v43
	v_cvt_pk_bf16_f32 v44, v44, v45
	v_cvt_pk_bf16_f32 v45, v46, v47
	global_store_dwordx2 v74, v[32:33], s[16:17] offset:0
	global_store_dwordx2 v74, v[36:37], s[16:17] offset:32
	global_store_dwordx2 v74, v[40:41], s[16:17] offset:64
	global_store_dwordx2 v74, v[44:45], s[16:17] offset:96
	ds_read_b128 v[32:35], v72 offset:6144
	ds_read_b128 v[36:39], v146 offset:6144
	ds_read_b128 v[40:43], v72 offset:8192
	s_waitcnt lgkmcnt(8)
	v_mfma_f32_16x16x32_bf16 v[78:81], v[48:51], v[8:11], 0
	ds_read_b128 v[44:47], v146 offset:8192
	s_waitcnt lgkmcnt(8)
	v_mfma_f32_16x16x32_bf16 v[78:81], v[52:55], v[12:15], v[78:81]
	ds_read_b128 v[48:51], v72 offset:10240
	s_waitcnt lgkmcnt(8)
	v_mfma_f32_16x16x32_bf16 v[82:85], v[56:59], v[8:11], 0
	ds_read_b128 v[52:55], v146 offset:10240
	s_waitcnt lgkmcnt(8)
	v_mfma_f32_16x16x32_bf16 v[82:85], v[60:63], v[12:15], v[82:85]
	ds_read_b128 v[56:59], v72 offset:12288
	s_waitcnt lgkmcnt(8)
	v_mfma_f32_16x16x32_bf16 v[86:89], v[64:67], v[8:11], 0
	ds_read_b128 v[60:63], v146 offset:12288
	s_waitcnt lgkmcnt(8)
	v_mfma_f32_16x16x32_bf16 v[86:89], v[68:71], v[12:15], v[86:89]
	ds_read_b128 v[64:67], v72 offset:14336
	s_waitcnt lgkmcnt(8)
	v_mfma_f32_16x16x32_bf16 v[90:93], v[32:35], v[8:11], 0
	ds_read_b128 v[68:71], v146 offset:14336
	s_waitcnt lgkmcnt(8)
	v_mfma_f32_16x16x32_bf16 v[90:93], v[36:39], v[12:15], v[90:93]
	ds_read_b128 v[32:35], v72 offset:16384
	s_waitcnt lgkmcnt(8)
	v_mfma_f32_16x16x32_bf16 v[94:97], v[40:43], v[8:11], 0
	ds_read_b128 v[36:39], v146 offset:16384
	s_waitcnt lgkmcnt(8)
	v_mfma_f32_16x16x32_bf16 v[94:97], v[44:47], v[12:15], v[94:97]
	ds_read_b128 v[40:43], v72 offset:18432
	s_waitcnt lgkmcnt(8)
	v_mfma_f32_16x16x32_bf16 v[98:101], v[48:51], v[8:11], 0
	ds_read_b128 v[44:47], v146 offset:18432
	s_waitcnt lgkmcnt(8)
	v_mfma_f32_16x16x32_bf16 v[98:101], v[52:55], v[12:15], v[98:101]
	ds_read_b128 v[48:51], v72 offset:20480
	s_waitcnt lgkmcnt(8)
	v_mfma_f32_16x16x32_bf16 v[102:105], v[56:59], v[8:11], 0
	ds_read_b128 v[52:55], v146 offset:20480
	s_waitcnt lgkmcnt(8)
	v_mfma_f32_16x16x32_bf16 v[102:105], v[60:63], v[12:15], v[102:105]
	ds_read_b128 v[56:59], v72 offset:22528
	s_waitcnt lgkmcnt(8)
	v_mfma_f32_16x16x32_bf16 v[106:109], v[64:67], v[8:11], 0
	ds_read_b128 v[60:63], v146 offset:22528
	s_waitcnt lgkmcnt(8)
	v_mfma_f32_16x16x32_bf16 v[106:109], v[68:71], v[12:15], v[106:109]
	ds_read_b128 v[64:67], v72 offset:24576
	s_waitcnt lgkmcnt(8)
	v_mfma_f32_16x16x32_bf16 v[110:113], v[32:35], v[8:11], 0
	ds_read_b128 v[68:71], v146 offset:24576
	s_waitcnt lgkmcnt(8)
	v_mfma_f32_16x16x32_bf16 v[110:113], v[36:39], v[12:15], v[110:113]
	ds_read_b128 v[32:35], v72 offset:26624
	s_waitcnt lgkmcnt(8)
	v_mfma_f32_16x16x32_bf16 v[114:117], v[40:43], v[8:11], 0
	ds_read_b128 v[36:39], v146 offset:26624
	s_waitcnt lgkmcnt(8)
	v_mfma_f32_16x16x32_bf16 v[114:117], v[44:47], v[12:15], v[114:117]
	ds_read_b128 v[40:43], v72 offset:28672
	s_waitcnt lgkmcnt(8)
	v_mfma_f32_16x16x32_bf16 v[118:121], v[48:51], v[8:11], 0
	ds_read_b128 v[44:47], v146 offset:28672
	s_waitcnt lgkmcnt(8)
	v_mfma_f32_16x16x32_bf16 v[118:121], v[52:55], v[12:15], v[118:121]
	ds_read_b128 v[48:51], v72 offset:30720
	s_waitcnt lgkmcnt(8)
	v_mfma_f32_16x16x32_bf16 v[122:125], v[56:59], v[8:11], 0
	ds_read_b128 v[52:55], v146 offset:30720
	s_waitcnt lgkmcnt(8)
	v_mfma_f32_16x16x32_bf16 v[122:125], v[60:63], v[12:15], v[122:125]
	s_waitcnt lgkmcnt(7)
	v_mfma_f32_16x16x32_bf16 v[126:129], v[64:67], v[8:11], 0
	s_waitcnt lgkmcnt(6)
	v_mfma_f32_16x16x32_bf16 v[126:129], v[68:71], v[12:15], v[126:129]
	s_waitcnt lgkmcnt(5)
	v_mfma_f32_16x16x32_bf16 v[130:133], v[32:35], v[8:11], 0
	s_waitcnt lgkmcnt(4)
	v_mfma_f32_16x16x32_bf16 v[130:133], v[36:39], v[12:15], v[130:133]
	s_waitcnt lgkmcnt(3)
	v_mfma_f32_16x16x32_bf16 v[134:137], v[40:43], v[8:11], 0
	s_waitcnt lgkmcnt(2)
	v_mfma_f32_16x16x32_bf16 v[134:137], v[44:47], v[12:15], v[134:137]
	s_waitcnt lgkmcnt(1)
	v_mfma_f32_16x16x32_bf16 v[138:141], v[48:51], v[8:11], 0
	s_waitcnt lgkmcnt(0)
	v_mfma_f32_16x16x32_bf16 v[138:141], v[52:55], v[12:15], v[138:141]
	ds_read_b64 v[48:49], v73 offset:36864
	ds_read_b64 v[50:51], v73 offset:36896
	ds_read_b64 v[52:53], v73 offset:45312
	ds_read_b64 v[54:55], v73 offset:45344
	ds_read_b64 v[56:57], v73 offset:53760
	ds_read_b64 v[58:59], v73 offset:53792
	ds_read_b64 v[60:61], v73 offset:62208
	ds_read_b64 v[62:63], v73 offset:62240
	ds_read_b64 v[64:65], v73 offset:36928
	ds_read_b64 v[66:67], v73 offset:36960
	ds_read_b64 v[68:69], v73 offset:45376
	ds_read_b64 v[70:71], v73 offset:45408
	v_max3_f32 v36, v78, v79, v80
	v_max3_f32 v36, v36, v81, v82
	v_max3_f32 v36, v36, v83, v84
	v_max3_f32 v36, v36, v85, v86
	v_max3_f32 v36, v36, v87, v88
	v_max3_f32 v36, v36, v89, v90
	v_max3_f32 v36, v36, v91, v92
	v_max3_f32 v36, v36, v93, v94
	v_max3_f32 v36, v36, v95, v96
	v_max3_f32 v36, v36, v97, v98
	v_max3_f32 v36, v36, v99, v100
	v_max3_f32 v36, v36, v101, v102
	v_max3_f32 v36, v36, v103, v104
	v_max3_f32 v36, v36, v105, v106
	v_max3_f32 v36, v36, v107, v108
	v_max3_f32 v36, v36, v109, v110
	v_max3_f32 v36, v36, v111, v112
	v_max3_f32 v36, v36, v113, v114
	v_max3_f32 v36, v36, v115, v116
	v_max3_f32 v36, v36, v117, v118
	v_max3_f32 v36, v36, v119, v120
	v_max3_f32 v36, v36, v121, v122
	v_max3_f32 v36, v36, v123, v124
	v_max3_f32 v36, v36, v125, v126
	v_max3_f32 v36, v36, v127, v128
	v_max3_f32 v36, v36, v129, v130
	v_max3_f32 v36, v36, v131, v132
	v_max3_f32 v36, v36, v133, v134
	v_max3_f32 v36, v36, v135, v136
	v_max3_f32 v36, v36, v137, v138
	v_max3_f32 v36, v36, v139, v140
	v_max_f32_e32 v36, v36, v141
	v_mov_b32_e32 v37, v36
	s_nop 1
	v_permlane16_swap_b32_e32 v36, v37
	v_max_f32_e32 v36, v36, v37
	v_mov_b32_e32 v37, v36
	s_nop 1
	v_permlane32_swap_b32_e32 v36, v37
	v_max_f32_e32 v36, v36, v37
	v_mul_f32_e64 v38, v36, -v144
	v_mov_b32_e32 v40, 0
	v_mov_b32_e32 v41, 0
	v_mov_b32_e32 v39, v38
	v_pk_fma_f32 v[78:79], v[78:79], v[144:145], v[38:39]
	v_pk_fma_f32 v[80:81], v[80:81], v[144:145], v[38:39]
	v_exp_f32_e32 v78, v78
	v_exp_f32_e32 v79, v79
	v_exp_f32_e32 v80, v80
	v_exp_f32_e32 v81, v81
	v_pk_fma_f32 v[82:83], v[82:83], v[144:145], v[38:39]
	v_pk_fma_f32 v[84:85], v[84:85], v[144:145], v[38:39]
	v_exp_f32_e32 v82, v82
	v_exp_f32_e32 v83, v83
	v_exp_f32_e32 v84, v84
	v_exp_f32_e32 v85, v85
	v_pk_add_f32 v[40:41], v[40:41], v[78:79]
	v_pk_add_f32 v[40:41], v[40:41], v[80:81]
	v_pk_fma_f32 v[86:87], v[86:87], v[144:145], v[38:39]
	v_pk_fma_f32 v[88:89], v[88:89], v[144:145], v[38:39]
	v_exp_f32_e32 v86, v86
	v_exp_f32_e32 v87, v87
	v_exp_f32_e32 v88, v88
	v_exp_f32_e32 v89, v89
	v_pk_add_f32 v[40:41], v[40:41], v[82:83]
	v_pk_add_f32 v[40:41], v[40:41], v[84:85]
	v_pk_fma_f32 v[90:91], v[90:91], v[144:145], v[38:39]
	v_pk_fma_f32 v[92:93], v[92:93], v[144:145], v[38:39]
	v_exp_f32_e32 v90, v90
	v_exp_f32_e32 v91, v91
	v_exp_f32_e32 v92, v92
	v_exp_f32_e32 v93, v93
	v_pk_add_f32 v[40:41], v[40:41], v[86:87]
	v_pk_add_f32 v[40:41], v[40:41], v[88:89]
	v_pk_fma_f32 v[94:95], v[94:95], v[144:145], v[38:39]
	v_pk_fma_f32 v[96:97], v[96:97], v[144:145], v[38:39]
	v_exp_f32_e32 v94, v94
	v_exp_f32_e32 v95, v95
	v_exp_f32_e32 v96, v96
	v_exp_f32_e32 v97, v97
	v_pk_add_f32 v[40:41], v[40:41], v[90:91]
	v_pk_add_f32 v[40:41], v[40:41], v[92:93]
	v_pk_fma_f32 v[98:99], v[98:99], v[144:145], v[38:39]
	v_pk_fma_f32 v[100:101], v[100:101], v[144:145], v[38:39]
	v_exp_f32_e32 v98, v98
	v_exp_f32_e32 v99, v99
	v_exp_f32_e32 v100, v100
	v_exp_f32_e32 v101, v101
	v_pk_add_f32 v[40:41], v[40:41], v[94:95]
	v_pk_add_f32 v[40:41], v[40:41], v[96:97]
	v_pk_fma_f32 v[102:103], v[102:103], v[144:145], v[38:39]
	v_pk_fma_f32 v[104:105], v[104:105], v[144:145], v[38:39]
	v_exp_f32_e32 v102, v102
	v_exp_f32_e32 v103, v103
	v_exp_f32_e32 v104, v104
	v_exp_f32_e32 v105, v105
	v_pk_add_f32 v[40:41], v[40:41], v[98:99]
	v_pk_add_f32 v[40:41], v[40:41], v[100:101]
	v_pk_fma_f32 v[106:107], v[106:107], v[144:145], v[38:39]
	v_pk_fma_f32 v[108:109], v[108:109], v[144:145], v[38:39]
	v_exp_f32_e32 v106, v106
	v_exp_f32_e32 v107, v107
	v_exp_f32_e32 v108, v108
	v_exp_f32_e32 v109, v109
	v_pk_add_f32 v[40:41], v[40:41], v[102:103]
	v_pk_add_f32 v[40:41], v[40:41], v[104:105]
	v_pk_fma_f32 v[110:111], v[110:111], v[144:145], v[38:39]
	v_pk_fma_f32 v[112:113], v[112:113], v[144:145], v[38:39]
	v_exp_f32_e32 v110, v110
	v_exp_f32_e32 v111, v111
	v_exp_f32_e32 v112, v112
	v_exp_f32_e32 v113, v113
	v_pk_add_f32 v[40:41], v[40:41], v[106:107]
	v_pk_add_f32 v[40:41], v[40:41], v[108:109]
	v_pk_fma_f32 v[114:115], v[114:115], v[144:145], v[38:39]
	v_pk_fma_f32 v[116:117], v[116:117], v[144:145], v[38:39]
	v_exp_f32_e32 v114, v114
	v_exp_f32_e32 v115, v115
	v_exp_f32_e32 v116, v116
	v_exp_f32_e32 v117, v117
	v_pk_add_f32 v[40:41], v[40:41], v[110:111]
	v_pk_add_f32 v[40:41], v[40:41], v[112:113]
	v_pk_fma_f32 v[118:119], v[118:119], v[144:145], v[38:39]
	v_pk_fma_f32 v[120:121], v[120:121], v[144:145], v[38:39]
	v_exp_f32_e32 v118, v118
	v_exp_f32_e32 v119, v119
	v_exp_f32_e32 v120, v120
	v_exp_f32_e32 v121, v121
	v_pk_add_f32 v[40:41], v[40:41], v[114:115]
	v_pk_add_f32 v[40:41], v[40:41], v[116:117]
	v_pk_fma_f32 v[122:123], v[122:123], v[144:145], v[38:39]
	v_pk_fma_f32 v[124:125], v[124:125], v[144:145], v[38:39]
	v_exp_f32_e32 v122, v122
	v_exp_f32_e32 v123, v123
	v_exp_f32_e32 v124, v124
	v_exp_f32_e32 v125, v125
	v_pk_add_f32 v[40:41], v[40:41], v[118:119]
	v_pk_add_f32 v[40:41], v[40:41], v[120:121]
	v_pk_fma_f32 v[126:127], v[126:127], v[144:145], v[38:39]
	v_pk_fma_f32 v[128:129], v[128:129], v[144:145], v[38:39]
	v_exp_f32_e32 v126, v126
	v_exp_f32_e32 v127, v127
	v_exp_f32_e32 v128, v128
	v_exp_f32_e32 v129, v129
	v_pk_add_f32 v[40:41], v[40:41], v[122:123]
	v_pk_add_f32 v[40:41], v[40:41], v[124:125]
	v_pk_fma_f32 v[130:131], v[130:131], v[144:145], v[38:39]
	v_pk_fma_f32 v[132:133], v[132:133], v[144:145], v[38:39]
	v_exp_f32_e32 v130, v130
	v_exp_f32_e32 v131, v131
	v_exp_f32_e32 v132, v132
	v_exp_f32_e32 v133, v133
	v_pk_add_f32 v[40:41], v[40:41], v[126:127]
	v_pk_add_f32 v[40:41], v[40:41], v[128:129]
	v_pk_fma_f32 v[134:135], v[134:135], v[144:145], v[38:39]
	v_pk_fma_f32 v[136:137], v[136:137], v[144:145], v[38:39]
	v_exp_f32_e32 v134, v134
	v_exp_f32_e32 v135, v135
	v_exp_f32_e32 v136, v136
	v_exp_f32_e32 v137, v137
	v_pk_add_f32 v[40:41], v[40:41], v[130:131]
	v_pk_add_f32 v[40:41], v[40:41], v[132:133]
	v_pk_fma_f32 v[138:139], v[138:139], v[144:145], v[38:39]
	v_pk_fma_f32 v[140:141], v[140:141], v[144:145], v[38:39]
	v_exp_f32_e32 v138, v138
	v_exp_f32_e32 v139, v139
	v_exp_f32_e32 v140, v140
	v_exp_f32_e32 v141, v141
	v_pk_add_f32 v[40:41], v[40:41], v[134:135]
	v_pk_add_f32 v[40:41], v[40:41], v[136:137]
	s_nop 0
	v_pk_add_f32 v[40:41], v[40:41], v[138:139]
	v_pk_add_f32 v[40:41], v[40:41], v[140:141]
	v_add_f32_e32 v36, v40, v41
	v_mov_b32_e32 v37, v36
	s_nop 1
	v_permlane16_swap_b32_e32 v36, v37
	v_add_f32_e32 v36, v36, v37
	v_mov_b32_e32 v37, v36
	s_nop 1
	v_permlane32_swap_b32_e32 v36, v37
	v_add_f32_e32 v36, v36, v37
	v_rcp_f32_e32 v142, v36
	v_cvt_pk_bf16_f32 v78, v78, v79
	v_cvt_pk_bf16_f32 v79, v80, v81
	v_cvt_pk_bf16_f32 v80, v82, v83
	v_cvt_pk_bf16_f32 v81, v84, v85
	v_cvt_pk_bf16_f32 v86, v86, v87
	v_cvt_pk_bf16_f32 v87, v88, v89
	v_cvt_pk_bf16_f32 v88, v90, v91
	v_cvt_pk_bf16_f32 v89, v92, v93
	v_cvt_pk_bf16_f32 v94, v94, v95
	v_cvt_pk_bf16_f32 v95, v96, v97
	v_cvt_pk_bf16_f32 v96, v98, v99
	v_cvt_pk_bf16_f32 v97, v100, v101
	v_cvt_pk_bf16_f32 v102, v102, v103
	v_cvt_pk_bf16_f32 v103, v104, v105
	v_cvt_pk_bf16_f32 v104, v106, v107
	v_cvt_pk_bf16_f32 v105, v108, v109
	v_cvt_pk_bf16_f32 v110, v110, v111
	v_cvt_pk_bf16_f32 v111, v112, v113
	v_cvt_pk_bf16_f32 v112, v114, v115
	v_cvt_pk_bf16_f32 v113, v116, v117
	v_cvt_pk_bf16_f32 v118, v118, v119
	v_cvt_pk_bf16_f32 v119, v120, v121
	v_cvt_pk_bf16_f32 v120, v122, v123
	v_cvt_pk_bf16_f32 v121, v124, v125
	v_cvt_pk_bf16_f32 v126, v126, v127
	v_cvt_pk_bf16_f32 v127, v128, v129
	v_cvt_pk_bf16_f32 v128, v130, v131
	v_cvt_pk_bf16_f32 v129, v132, v133
	v_cvt_pk_bf16_f32 v134, v134, v135
	v_cvt_pk_bf16_f32 v135, v136, v137
	v_cvt_pk_bf16_f32 v136, v138, v139
	v_cvt_pk_bf16_f32 v137, v140, v141
	v_fma_f32 v143, -v36, v142, 1.0
	v_fma_f32 v142, v143, v142, v142
	v_mov_b32_e32 v143, v142
	ds_read_b64 v[82:83], v73 offset:53824
	ds_read_b64 v[84:85], v73 offset:53856
	s_waitcnt lgkmcnt(12)
	v_mfma_f32_16x16x32_bf16 v[32:35], v[48:51], v[78:81], 0
	ds_read_b64 v[90:91], v73 offset:62272
	ds_read_b64 v[92:93], v73 offset:62304
	s_waitcnt lgkmcnt(12)
	v_mfma_f32_16x16x32_bf16 v[36:39], v[52:55], v[78:81], 0
	ds_read_b64 v[48:49], v73 offset:36992
	ds_read_b64 v[50:51], v73 offset:37024
	s_waitcnt lgkmcnt(12)
	v_mfma_f32_16x16x32_bf16 v[40:43], v[56:59], v[78:81], 0
	ds_read_b64 v[52:53], v73 offset:45440
	ds_read_b64 v[54:55], v73 offset:45472
	s_waitcnt lgkmcnt(12)
	v_mfma_f32_16x16x32_bf16 v[44:47], v[60:63], v[78:81], 0
	ds_read_b64 v[56:57], v73 offset:53888
	ds_read_b64 v[58:59], v73 offset:53920
	s_waitcnt lgkmcnt(12)
	v_mfma_f32_16x16x32_bf16 v[32:35], v[64:67], v[86:89], v[32:35]
	ds_read_b64 v[60:61], v73 offset:62336
	ds_read_b64 v[62:63], v73 offset:62368
	s_waitcnt lgkmcnt(12)
	v_mfma_f32_16x16x32_bf16 v[36:39], v[68:71], v[86:89], v[36:39]
	ds_read_b64 v[64:65], v73 offset:37056
	ds_read_b64 v[66:67], v73 offset:37088
	s_waitcnt lgkmcnt(12)
	v_mfma_f32_16x16x32_bf16 v[40:43], v[82:85], v[86:89], v[40:43]
	ds_read_b64 v[68:69], v73 offset:45504
	ds_read_b64 v[70:71], v73 offset:45536
	s_waitcnt lgkmcnt(12)
	v_mfma_f32_16x16x32_bf16 v[44:47], v[90:93], v[86:89], v[44:47]
	ds_read_b64 v[82:83], v73 offset:53952
	ds_read_b64 v[84:85], v73 offset:53984
	s_waitcnt lgkmcnt(12)
	v_mfma_f32_16x16x32_bf16 v[32:35], v[48:51], v[94:97], v[32:35]
	ds_read_b64 v[90:91], v73 offset:62400
	ds_read_b64 v[92:93], v73 offset:62432
	s_waitcnt lgkmcnt(12)
	v_mfma_f32_16x16x32_bf16 v[36:39], v[52:55], v[94:97], v[36:39]
	ds_read_b64 v[48:49], v73 offset:37120
	ds_read_b64 v[50:51], v73 offset:37152
	s_waitcnt lgkmcnt(12)
	v_mfma_f32_16x16x32_bf16 v[40:43], v[56:59], v[94:97], v[40:43]
	ds_read_b64 v[52:53], v73 offset:45568
	ds_read_b64 v[54:55], v73 offset:45600
	s_waitcnt lgkmcnt(12)
	v_mfma_f32_16x16x32_bf16 v[44:47], v[60:63], v[94:97], v[44:47]
	ds_read_b64 v[56:57], v73 offset:54016
	ds_read_b64 v[58:59], v73 offset:54048
	s_waitcnt lgkmcnt(12)
	v_mfma_f32_16x16x32_bf16 v[32:35], v[64:67], v[102:105], v[32:35]
	ds_read_b64 v[60:61], v73 offset:62464
	ds_read_b64 v[62:63], v73 offset:62496
	s_waitcnt lgkmcnt(12)
	v_mfma_f32_16x16x32_bf16 v[36:39], v[68:71], v[102:105], v[36:39]
	ds_read_b64 v[64:65], v73 offset:37184
	ds_read_b64 v[66:67], v73 offset:37216
	s_waitcnt lgkmcnt(12)
	v_mfma_f32_16x16x32_bf16 v[40:43], v[82:85], v[102:105], v[40:43]
	ds_read_b64 v[68:69], v73 offset:45632
	ds_read_b64 v[70:71], v73 offset:45664
	s_waitcnt lgkmcnt(12)
	v_mfma_f32_16x16x32_bf16 v[44:47], v[90:93], v[102:105], v[44:47]
	ds_read_b64 v[82:83], v73 offset:54080
	ds_read_b64 v[84:85], v73 offset:54112
	s_waitcnt lgkmcnt(12)
	v_mfma_f32_16x16x32_bf16 v[32:35], v[48:51], v[110:113], v[32:35]
	ds_read_b64 v[90:91], v73 offset:62528
	ds_read_b64 v[92:93], v73 offset:62560
	s_waitcnt lgkmcnt(12)
	v_mfma_f32_16x16x32_bf16 v[36:39], v[52:55], v[110:113], v[36:39]
	ds_read_b64 v[48:49], v73 offset:37248
	ds_read_b64 v[50:51], v73 offset:37280
	s_waitcnt lgkmcnt(12)
	v_mfma_f32_16x16x32_bf16 v[40:43], v[56:59], v[110:113], v[40:43]
	ds_read_b64 v[52:53], v73 offset:45696
	ds_read_b64 v[54:55], v73 offset:45728
	s_waitcnt lgkmcnt(12)
	v_mfma_f32_16x16x32_bf16 v[44:47], v[60:63], v[110:113], v[44:47]
	ds_read_b64 v[56:57], v73 offset:54144
	ds_read_b64 v[58:59], v73 offset:54176
	s_waitcnt lgkmcnt(12)
	v_mfma_f32_16x16x32_bf16 v[32:35], v[64:67], v[118:121], v[32:35]
	ds_read_b64 v[60:61], v73 offset:62592
	ds_read_b64 v[62:63], v73 offset:62624
	s_waitcnt lgkmcnt(12)
	v_mfma_f32_16x16x32_bf16 v[36:39], v[68:71], v[118:121], v[36:39]
	ds_read_b64 v[64:65], v73 offset:37312
	ds_read_b64 v[66:67], v73 offset:37344
	s_waitcnt lgkmcnt(12)
	v_mfma_f32_16x16x32_bf16 v[40:43], v[82:85], v[118:121], v[40:43]
	ds_read_b64 v[68:69], v73 offset:45760
	ds_read_b64 v[70:71], v73 offset:45792
	s_waitcnt lgkmcnt(12)
	v_mfma_f32_16x16x32_bf16 v[44:47], v[90:93], v[118:121], v[44:47]
	ds_read_b64 v[82:83], v73 offset:54208
	ds_read_b64 v[84:85], v73 offset:54240
	s_waitcnt lgkmcnt(12)
	v_mfma_f32_16x16x32_bf16 v[32:35], v[48:51], v[126:129], v[32:35]
	ds_read_b64 v[90:91], v73 offset:62656
	ds_read_b64 v[92:93], v73 offset:62688
	s_waitcnt lgkmcnt(12)
	v_mfma_f32_16x16x32_bf16 v[36:39], v[52:55], v[126:129], v[36:39]
	s_waitcnt lgkmcnt(10)
	v_mfma_f32_16x16x32_bf16 v[40:43], v[56:59], v[126:129], v[40:43]
	s_waitcnt lgkmcnt(8)
	v_mfma_f32_16x16x32_bf16 v[44:47], v[60:63], v[126:129], v[44:47]
	s_waitcnt lgkmcnt(6)
	v_mfma_f32_16x16x32_bf16 v[32:35], v[64:67], v[134:137], v[32:35]
	s_waitcnt lgkmcnt(4)
	v_mfma_f32_16x16x32_bf16 v[36:39], v[68:71], v[134:137], v[36:39]
	s_waitcnt lgkmcnt(2)
	v_mfma_f32_16x16x32_bf16 v[40:43], v[82:85], v[134:137], v[40:43]
	s_waitcnt lgkmcnt(0)
	v_mfma_f32_16x16x32_bf16 v[44:47], v[90:93], v[134:137], v[44:47]
	ds_read_b128 v[48:51], v72 offset:0
	ds_read_b128 v[52:55], v146 offset:0
	ds_read_b128 v[56:59], v72 offset:2048
	ds_read_b128 v[60:63], v146 offset:2048
	ds_read_b128 v[64:67], v72 offset:4096
	ds_read_b128 v[68:71], v146 offset:4096
	s_add_u32 s16, s12, 0x8000
	s_addc_u32 s17, s13, 0
	s_nop 7
	v_pk_mul_f32 v[32:33], v[32:33], v[142:143]
	v_pk_mul_f32 v[34:35], v[34:35], v[142:143]
	v_pk_mul_f32 v[36:37], v[36:37], v[142:143]
	v_pk_mul_f32 v[38:39], v[38:39], v[142:143]
	v_pk_mul_f32 v[40:41], v[40:41], v[142:143]
	v_pk_mul_f32 v[42:43], v[42:43], v[142:143]
	v_pk_mul_f32 v[44:45], v[44:45], v[142:143]
	v_pk_mul_f32 v[46:47], v[46:47], v[142:143]
	v_cvt_pk_bf16_f32 v32, v32, v33
	v_cvt_pk_bf16_f32 v33, v34, v35
	v_cvt_pk_bf16_f32 v36, v36, v37
	v_cvt_pk_bf16_f32 v37, v38, v39
	v_cvt_pk_bf16_f32 v40, v40, v41
	v_cvt_pk_bf16_f32 v41, v42, v43
	v_cvt_pk_bf16_f32 v44, v44, v45
	v_cvt_pk_bf16_f32 v45, v46, v47
	global_store_dwordx2 v74, v[32:33], s[16:17] offset:0
	global_store_dwordx2 v74, v[36:37], s[16:17] offset:32
	global_store_dwordx2 v74, v[40:41], s[16:17] offset:64
	global_store_dwordx2 v74, v[44:45], s[16:17] offset:96
	ds_read_b128 v[32:35], v72 offset:6144
	ds_read_b128 v[36:39], v146 offset:6144
	ds_read_b128 v[40:43], v72 offset:8192
	s_waitcnt lgkmcnt(8)
	v_mfma_f32_16x16x32_bf16 v[78:81], v[48:51], v[16:19], 0
	ds_read_b128 v[44:47], v146 offset:8192
	s_waitcnt lgkmcnt(8)
	v_mfma_f32_16x16x32_bf16 v[78:81], v[52:55], v[20:23], v[78:81]
	ds_read_b128 v[48:51], v72 offset:10240
	s_waitcnt lgkmcnt(8)
	v_mfma_f32_16x16x32_bf16 v[82:85], v[56:59], v[16:19], 0
	ds_read_b128 v[52:55], v146 offset:10240
	s_waitcnt lgkmcnt(8)
	v_mfma_f32_16x16x32_bf16 v[82:85], v[60:63], v[20:23], v[82:85]
	ds_read_b128 v[56:59], v72 offset:12288
	s_waitcnt lgkmcnt(8)
	v_mfma_f32_16x16x32_bf16 v[86:89], v[64:67], v[16:19], 0
	ds_read_b128 v[60:63], v146 offset:12288
	s_waitcnt lgkmcnt(8)
	v_mfma_f32_16x16x32_bf16 v[86:89], v[68:71], v[20:23], v[86:89]
	ds_read_b128 v[64:67], v72 offset:14336
	s_waitcnt lgkmcnt(8)
	v_mfma_f32_16x16x32_bf16 v[90:93], v[32:35], v[16:19], 0
	ds_read_b128 v[68:71], v146 offset:14336
	s_waitcnt lgkmcnt(8)
	v_mfma_f32_16x16x32_bf16 v[90:93], v[36:39], v[20:23], v[90:93]
	ds_read_b128 v[32:35], v72 offset:16384
	s_waitcnt lgkmcnt(8)
	v_mfma_f32_16x16x32_bf16 v[94:97], v[40:43], v[16:19], 0
	ds_read_b128 v[36:39], v146 offset:16384
	s_waitcnt lgkmcnt(8)
	v_mfma_f32_16x16x32_bf16 v[94:97], v[44:47], v[20:23], v[94:97]
	ds_read_b128 v[40:43], v72 offset:18432
	s_waitcnt lgkmcnt(8)
	v_mfma_f32_16x16x32_bf16 v[98:101], v[48:51], v[16:19], 0
	ds_read_b128 v[44:47], v146 offset:18432
	s_waitcnt lgkmcnt(8)
	v_mfma_f32_16x16x32_bf16 v[98:101], v[52:55], v[20:23], v[98:101]
	ds_read_b128 v[48:51], v72 offset:20480
	s_waitcnt lgkmcnt(8)
	v_mfma_f32_16x16x32_bf16 v[102:105], v[56:59], v[16:19], 0
	ds_read_b128 v[52:55], v146 offset:20480
	s_waitcnt lgkmcnt(8)
	v_mfma_f32_16x16x32_bf16 v[102:105], v[60:63], v[20:23], v[102:105]
	ds_read_b128 v[56:59], v72 offset:22528
	s_waitcnt lgkmcnt(8)
	v_mfma_f32_16x16x32_bf16 v[106:109], v[64:67], v[16:19], 0
	ds_read_b128 v[60:63], v146 offset:22528
	s_waitcnt lgkmcnt(8)
	v_mfma_f32_16x16x32_bf16 v[106:109], v[68:71], v[20:23], v[106:109]
	ds_read_b128 v[64:67], v72 offset:24576
	s_waitcnt lgkmcnt(8)
	v_mfma_f32_16x16x32_bf16 v[110:113], v[32:35], v[16:19], 0
	ds_read_b128 v[68:71], v146 offset:24576
	s_waitcnt lgkmcnt(8)
	v_mfma_f32_16x16x32_bf16 v[110:113], v[36:39], v[20:23], v[110:113]
	ds_read_b128 v[32:35], v72 offset:26624
	s_waitcnt lgkmcnt(8)
	v_mfma_f32_16x16x32_bf16 v[114:117], v[40:43], v[16:19], 0
	ds_read_b128 v[36:39], v146 offset:26624
	s_waitcnt lgkmcnt(8)
	v_mfma_f32_16x16x32_bf16 v[114:117], v[44:47], v[20:23], v[114:117]
	ds_read_b128 v[40:43], v72 offset:28672
	s_waitcnt lgkmcnt(8)
	v_mfma_f32_16x16x32_bf16 v[118:121], v[48:51], v[16:19], 0
	ds_read_b128 v[44:47], v146 offset:28672
	s_waitcnt lgkmcnt(8)
	v_mfma_f32_16x16x32_bf16 v[118:121], v[52:55], v[20:23], v[118:121]
	ds_read_b128 v[48:51], v72 offset:30720
	s_waitcnt lgkmcnt(8)
	v_mfma_f32_16x16x32_bf16 v[122:125], v[56:59], v[16:19], 0
	ds_read_b128 v[52:55], v146 offset:30720
	s_waitcnt lgkmcnt(8)
	v_mfma_f32_16x16x32_bf16 v[122:125], v[60:63], v[20:23], v[122:125]
	s_waitcnt lgkmcnt(7)
	v_mfma_f32_16x16x32_bf16 v[126:129], v[64:67], v[16:19], 0
	s_waitcnt lgkmcnt(6)
	v_mfma_f32_16x16x32_bf16 v[126:129], v[68:71], v[20:23], v[126:129]
	s_waitcnt lgkmcnt(5)
	v_mfma_f32_16x16x32_bf16 v[130:133], v[32:35], v[16:19], 0
	s_waitcnt lgkmcnt(4)
	v_mfma_f32_16x16x32_bf16 v[130:133], v[36:39], v[20:23], v[130:133]
	s_waitcnt lgkmcnt(3)
	v_mfma_f32_16x16x32_bf16 v[134:137], v[40:43], v[16:19], 0
	s_waitcnt lgkmcnt(2)
	v_mfma_f32_16x16x32_bf16 v[134:137], v[44:47], v[20:23], v[134:137]
	s_waitcnt lgkmcnt(1)
	v_mfma_f32_16x16x32_bf16 v[138:141], v[48:51], v[16:19], 0
	s_waitcnt lgkmcnt(0)
	v_mfma_f32_16x16x32_bf16 v[138:141], v[52:55], v[20:23], v[138:141]
	ds_read_b64 v[48:49], v73 offset:36864
	ds_read_b64 v[50:51], v73 offset:36896
	ds_read_b64 v[52:53], v73 offset:45312
	ds_read_b64 v[54:55], v73 offset:45344
	ds_read_b64 v[56:57], v73 offset:53760
	ds_read_b64 v[58:59], v73 offset:53792
	ds_read_b64 v[60:61], v73 offset:62208
	ds_read_b64 v[62:63], v73 offset:62240
	ds_read_b64 v[64:65], v73 offset:36928
	ds_read_b64 v[66:67], v73 offset:36960
	ds_read_b64 v[68:69], v73 offset:45376
	ds_read_b64 v[70:71], v73 offset:45408
	v_max3_f32 v36, v78, v79, v80
	v_max3_f32 v36, v36, v81, v82
	v_max3_f32 v36, v36, v83, v84
	v_max3_f32 v36, v36, v85, v86
	v_max3_f32 v36, v36, v87, v88
	v_max3_f32 v36, v36, v89, v90
	v_max3_f32 v36, v36, v91, v92
	v_max3_f32 v36, v36, v93, v94
	v_max3_f32 v36, v36, v95, v96
	v_max3_f32 v36, v36, v97, v98
	v_max3_f32 v36, v36, v99, v100
	v_max3_f32 v36, v36, v101, v102
	v_max3_f32 v36, v36, v103, v104
	v_max3_f32 v36, v36, v105, v106
	v_max3_f32 v36, v36, v107, v108
	v_max3_f32 v36, v36, v109, v110
	v_max3_f32 v36, v36, v111, v112
	v_max3_f32 v36, v36, v113, v114
	v_max3_f32 v36, v36, v115, v116
	v_max3_f32 v36, v36, v117, v118
	v_max3_f32 v36, v36, v119, v120
	v_max3_f32 v36, v36, v121, v122
	v_max3_f32 v36, v36, v123, v124
	v_max3_f32 v36, v36, v125, v126
	v_max3_f32 v36, v36, v127, v128
	v_max3_f32 v36, v36, v129, v130
	v_max3_f32 v36, v36, v131, v132
	v_max3_f32 v36, v36, v133, v134
	v_max3_f32 v36, v36, v135, v136
	v_max3_f32 v36, v36, v137, v138
	v_max3_f32 v36, v36, v139, v140
	v_max_f32_e32 v36, v36, v141
	v_mov_b32_e32 v37, v36
	s_nop 1
	v_permlane16_swap_b32_e32 v36, v37
	v_max_f32_e32 v36, v36, v37
	v_mov_b32_e32 v37, v36
	s_nop 1
	v_permlane32_swap_b32_e32 v36, v37
	v_max_f32_e32 v36, v36, v37
	v_mul_f32_e64 v38, v36, -v144
	v_mov_b32_e32 v40, 0
	v_mov_b32_e32 v41, 0
	v_mov_b32_e32 v39, v38
	v_pk_fma_f32 v[78:79], v[78:79], v[144:145], v[38:39]
	v_pk_fma_f32 v[80:81], v[80:81], v[144:145], v[38:39]
	v_exp_f32_e32 v78, v78
	v_exp_f32_e32 v79, v79
	v_exp_f32_e32 v80, v80
	v_exp_f32_e32 v81, v81
	v_pk_fma_f32 v[82:83], v[82:83], v[144:145], v[38:39]
	v_pk_fma_f32 v[84:85], v[84:85], v[144:145], v[38:39]
	v_exp_f32_e32 v82, v82
	v_exp_f32_e32 v83, v83
	v_exp_f32_e32 v84, v84
	v_exp_f32_e32 v85, v85
	v_pk_add_f32 v[40:41], v[40:41], v[78:79]
	v_pk_add_f32 v[40:41], v[40:41], v[80:81]
	v_pk_fma_f32 v[86:87], v[86:87], v[144:145], v[38:39]
	v_pk_fma_f32 v[88:89], v[88:89], v[144:145], v[38:39]
	v_exp_f32_e32 v86, v86
	v_exp_f32_e32 v87, v87
	v_exp_f32_e32 v88, v88
	v_exp_f32_e32 v89, v89
	v_pk_add_f32 v[40:41], v[40:41], v[82:83]
	v_pk_add_f32 v[40:41], v[40:41], v[84:85]
	v_pk_fma_f32 v[90:91], v[90:91], v[144:145], v[38:39]
	v_pk_fma_f32 v[92:93], v[92:93], v[144:145], v[38:39]
	v_exp_f32_e32 v90, v90
	v_exp_f32_e32 v91, v91
	v_exp_f32_e32 v92, v92
	v_exp_f32_e32 v93, v93
	v_pk_add_f32 v[40:41], v[40:41], v[86:87]
	v_pk_add_f32 v[40:41], v[40:41], v[88:89]
	v_pk_fma_f32 v[94:95], v[94:95], v[144:145], v[38:39]
	v_pk_fma_f32 v[96:97], v[96:97], v[144:145], v[38:39]
	v_exp_f32_e32 v94, v94
	v_exp_f32_e32 v95, v95
	v_exp_f32_e32 v96, v96
	v_exp_f32_e32 v97, v97
	v_pk_add_f32 v[40:41], v[40:41], v[90:91]
	v_pk_add_f32 v[40:41], v[40:41], v[92:93]
	v_pk_fma_f32 v[98:99], v[98:99], v[144:145], v[38:39]
	v_pk_fma_f32 v[100:101], v[100:101], v[144:145], v[38:39]
	v_exp_f32_e32 v98, v98
	v_exp_f32_e32 v99, v99
	v_exp_f32_e32 v100, v100
	v_exp_f32_e32 v101, v101
	v_pk_add_f32 v[40:41], v[40:41], v[94:95]
	v_pk_add_f32 v[40:41], v[40:41], v[96:97]
	v_pk_fma_f32 v[102:103], v[102:103], v[144:145], v[38:39]
	v_pk_fma_f32 v[104:105], v[104:105], v[144:145], v[38:39]
	v_exp_f32_e32 v102, v102
	v_exp_f32_e32 v103, v103
	v_exp_f32_e32 v104, v104
	v_exp_f32_e32 v105, v105
	v_pk_add_f32 v[40:41], v[40:41], v[98:99]
	v_pk_add_f32 v[40:41], v[40:41], v[100:101]
	v_pk_fma_f32 v[106:107], v[106:107], v[144:145], v[38:39]
	v_pk_fma_f32 v[108:109], v[108:109], v[144:145], v[38:39]
	v_exp_f32_e32 v106, v106
	v_exp_f32_e32 v107, v107
	v_exp_f32_e32 v108, v108
	v_exp_f32_e32 v109, v109
	v_pk_add_f32 v[40:41], v[40:41], v[102:103]
	v_pk_add_f32 v[40:41], v[40:41], v[104:105]
	v_pk_fma_f32 v[110:111], v[110:111], v[144:145], v[38:39]
	v_pk_fma_f32 v[112:113], v[112:113], v[144:145], v[38:39]
	v_exp_f32_e32 v110, v110
	v_exp_f32_e32 v111, v111
	v_exp_f32_e32 v112, v112
	v_exp_f32_e32 v113, v113
	v_pk_add_f32 v[40:41], v[40:41], v[106:107]
	v_pk_add_f32 v[40:41], v[40:41], v[108:109]
	v_pk_fma_f32 v[114:115], v[114:115], v[144:145], v[38:39]
	v_pk_fma_f32 v[116:117], v[116:117], v[144:145], v[38:39]
	v_exp_f32_e32 v114, v114
	v_exp_f32_e32 v115, v115
	v_exp_f32_e32 v116, v116
	v_exp_f32_e32 v117, v117
	v_pk_add_f32 v[40:41], v[40:41], v[110:111]
	v_pk_add_f32 v[40:41], v[40:41], v[112:113]
	v_pk_fma_f32 v[118:119], v[118:119], v[144:145], v[38:39]
	v_pk_fma_f32 v[120:121], v[120:121], v[144:145], v[38:39]
	v_exp_f32_e32 v118, v118
	v_exp_f32_e32 v119, v119
	v_exp_f32_e32 v120, v120
	v_exp_f32_e32 v121, v121
	v_pk_add_f32 v[40:41], v[40:41], v[114:115]
	v_pk_add_f32 v[40:41], v[40:41], v[116:117]
	v_pk_fma_f32 v[122:123], v[122:123], v[144:145], v[38:39]
	v_pk_fma_f32 v[124:125], v[124:125], v[144:145], v[38:39]
	v_exp_f32_e32 v122, v122
	v_exp_f32_e32 v123, v123
	v_exp_f32_e32 v124, v124
	v_exp_f32_e32 v125, v125
	v_pk_add_f32 v[40:41], v[40:41], v[118:119]
	v_pk_add_f32 v[40:41], v[40:41], v[120:121]
	v_pk_fma_f32 v[126:127], v[126:127], v[144:145], v[38:39]
	v_pk_fma_f32 v[128:129], v[128:129], v[144:145], v[38:39]
	v_exp_f32_e32 v126, v126
	v_exp_f32_e32 v127, v127
	v_exp_f32_e32 v128, v128
	v_exp_f32_e32 v129, v129
	v_pk_add_f32 v[40:41], v[40:41], v[122:123]
	v_pk_add_f32 v[40:41], v[40:41], v[124:125]
	v_pk_fma_f32 v[130:131], v[130:131], v[144:145], v[38:39]
	v_pk_fma_f32 v[132:133], v[132:133], v[144:145], v[38:39]
	v_exp_f32_e32 v130, v130
	v_exp_f32_e32 v131, v131
	v_exp_f32_e32 v132, v132
	v_exp_f32_e32 v133, v133
	v_pk_add_f32 v[40:41], v[40:41], v[126:127]
	v_pk_add_f32 v[40:41], v[40:41], v[128:129]
	v_pk_fma_f32 v[134:135], v[134:135], v[144:145], v[38:39]
	v_pk_fma_f32 v[136:137], v[136:137], v[144:145], v[38:39]
	v_exp_f32_e32 v134, v134
	v_exp_f32_e32 v135, v135
	v_exp_f32_e32 v136, v136
	v_exp_f32_e32 v137, v137
	v_pk_add_f32 v[40:41], v[40:41], v[130:131]
	v_pk_add_f32 v[40:41], v[40:41], v[132:133]
	v_pk_fma_f32 v[138:139], v[138:139], v[144:145], v[38:39]
	v_pk_fma_f32 v[140:141], v[140:141], v[144:145], v[38:39]
	v_exp_f32_e32 v138, v138
	v_exp_f32_e32 v139, v139
	v_exp_f32_e32 v140, v140
	v_exp_f32_e32 v141, v141
	v_pk_add_f32 v[40:41], v[40:41], v[134:135]
	v_pk_add_f32 v[40:41], v[40:41], v[136:137]
	s_nop 0
	v_pk_add_f32 v[40:41], v[40:41], v[138:139]
	v_pk_add_f32 v[40:41], v[40:41], v[140:141]
	v_add_f32_e32 v36, v40, v41
	v_mov_b32_e32 v37, v36
	s_nop 1
	v_permlane16_swap_b32_e32 v36, v37
	v_add_f32_e32 v36, v36, v37
	v_mov_b32_e32 v37, v36
	s_nop 1
	v_permlane32_swap_b32_e32 v36, v37
	v_add_f32_e32 v36, v36, v37
	v_rcp_f32_e32 v142, v36
	v_cvt_pk_bf16_f32 v78, v78, v79
	v_cvt_pk_bf16_f32 v79, v80, v81
	v_cvt_pk_bf16_f32 v80, v82, v83
	v_cvt_pk_bf16_f32 v81, v84, v85
	v_cvt_pk_bf16_f32 v86, v86, v87
	v_cvt_pk_bf16_f32 v87, v88, v89
	v_cvt_pk_bf16_f32 v88, v90, v91
	v_cvt_pk_bf16_f32 v89, v92, v93
	v_cvt_pk_bf16_f32 v94, v94, v95
	v_cvt_pk_bf16_f32 v95, v96, v97
	v_cvt_pk_bf16_f32 v96, v98, v99
	v_cvt_pk_bf16_f32 v97, v100, v101
	v_cvt_pk_bf16_f32 v102, v102, v103
	v_cvt_pk_bf16_f32 v103, v104, v105
	v_cvt_pk_bf16_f32 v104, v106, v107
	v_cvt_pk_bf16_f32 v105, v108, v109
	v_cvt_pk_bf16_f32 v110, v110, v111
	v_cvt_pk_bf16_f32 v111, v112, v113
	v_cvt_pk_bf16_f32 v112, v114, v115
	v_cvt_pk_bf16_f32 v113, v116, v117
	v_cvt_pk_bf16_f32 v118, v118, v119
	v_cvt_pk_bf16_f32 v119, v120, v121
	v_cvt_pk_bf16_f32 v120, v122, v123
	v_cvt_pk_bf16_f32 v121, v124, v125
	v_cvt_pk_bf16_f32 v126, v126, v127
	v_cvt_pk_bf16_f32 v127, v128, v129
	v_cvt_pk_bf16_f32 v128, v130, v131
	v_cvt_pk_bf16_f32 v129, v132, v133
	v_cvt_pk_bf16_f32 v134, v134, v135
	v_cvt_pk_bf16_f32 v135, v136, v137
	v_cvt_pk_bf16_f32 v136, v138, v139
	v_cvt_pk_bf16_f32 v137, v140, v141
	v_fma_f32 v143, -v36, v142, 1.0
	v_fma_f32 v142, v143, v142, v142
	v_mov_b32_e32 v143, v142
	ds_read_b64 v[82:83], v73 offset:53824
	ds_read_b64 v[84:85], v73 offset:53856
	s_waitcnt lgkmcnt(12)
	v_mfma_f32_16x16x32_bf16 v[32:35], v[48:51], v[78:81], 0
	ds_read_b64 v[90:91], v73 offset:62272
	ds_read_b64 v[92:93], v73 offset:62304
	s_waitcnt lgkmcnt(12)
	v_mfma_f32_16x16x32_bf16 v[36:39], v[52:55], v[78:81], 0
	ds_read_b64 v[48:49], v73 offset:36992
	ds_read_b64 v[50:51], v73 offset:37024
	s_waitcnt lgkmcnt(12)
	v_mfma_f32_16x16x32_bf16 v[40:43], v[56:59], v[78:81], 0
	ds_read_b64 v[52:53], v73 offset:45440
	ds_read_b64 v[54:55], v73 offset:45472
	s_waitcnt lgkmcnt(12)
	v_mfma_f32_16x16x32_bf16 v[44:47], v[60:63], v[78:81], 0
	ds_read_b64 v[56:57], v73 offset:53888
	ds_read_b64 v[58:59], v73 offset:53920
	s_waitcnt lgkmcnt(12)
	v_mfma_f32_16x16x32_bf16 v[32:35], v[64:67], v[86:89], v[32:35]
	ds_read_b64 v[60:61], v73 offset:62336
	ds_read_b64 v[62:63], v73 offset:62368
	s_waitcnt lgkmcnt(12)
	v_mfma_f32_16x16x32_bf16 v[36:39], v[68:71], v[86:89], v[36:39]
	ds_read_b64 v[64:65], v73 offset:37056
	ds_read_b64 v[66:67], v73 offset:37088
	s_waitcnt lgkmcnt(12)
	v_mfma_f32_16x16x32_bf16 v[40:43], v[82:85], v[86:89], v[40:43]
	ds_read_b64 v[68:69], v73 offset:45504
	ds_read_b64 v[70:71], v73 offset:45536
	s_waitcnt lgkmcnt(12)
	v_mfma_f32_16x16x32_bf16 v[44:47], v[90:93], v[86:89], v[44:47]
	ds_read_b64 v[82:83], v73 offset:53952
	ds_read_b64 v[84:85], v73 offset:53984
	s_waitcnt lgkmcnt(12)
	v_mfma_f32_16x16x32_bf16 v[32:35], v[48:51], v[94:97], v[32:35]
	ds_read_b64 v[90:91], v73 offset:62400
	ds_read_b64 v[92:93], v73 offset:62432
	s_waitcnt lgkmcnt(12)
	v_mfma_f32_16x16x32_bf16 v[36:39], v[52:55], v[94:97], v[36:39]
	ds_read_b64 v[48:49], v73 offset:37120
	ds_read_b64 v[50:51], v73 offset:37152
	s_waitcnt lgkmcnt(12)
	v_mfma_f32_16x16x32_bf16 v[40:43], v[56:59], v[94:97], v[40:43]
	ds_read_b64 v[52:53], v73 offset:45568
	ds_read_b64 v[54:55], v73 offset:45600
	s_waitcnt lgkmcnt(12)
	v_mfma_f32_16x16x32_bf16 v[44:47], v[60:63], v[94:97], v[44:47]
	ds_read_b64 v[56:57], v73 offset:54016
	ds_read_b64 v[58:59], v73 offset:54048
	s_waitcnt lgkmcnt(12)
	v_mfma_f32_16x16x32_bf16 v[32:35], v[64:67], v[102:105], v[32:35]
	ds_read_b64 v[60:61], v73 offset:62464
	ds_read_b64 v[62:63], v73 offset:62496
	s_waitcnt lgkmcnt(12)
	v_mfma_f32_16x16x32_bf16 v[36:39], v[68:71], v[102:105], v[36:39]
	ds_read_b64 v[64:65], v73 offset:37184
	ds_read_b64 v[66:67], v73 offset:37216
	s_waitcnt lgkmcnt(12)
	v_mfma_f32_16x16x32_bf16 v[40:43], v[82:85], v[102:105], v[40:43]
	ds_read_b64 v[68:69], v73 offset:45632
	ds_read_b64 v[70:71], v73 offset:45664
	s_waitcnt lgkmcnt(12)
	v_mfma_f32_16x16x32_bf16 v[44:47], v[90:93], v[102:105], v[44:47]
	ds_read_b64 v[82:83], v73 offset:54080
	ds_read_b64 v[84:85], v73 offset:54112
	s_waitcnt lgkmcnt(12)
	v_mfma_f32_16x16x32_bf16 v[32:35], v[48:51], v[110:113], v[32:35]
	ds_read_b64 v[90:91], v73 offset:62528
	ds_read_b64 v[92:93], v73 offset:62560
	s_waitcnt lgkmcnt(12)
	v_mfma_f32_16x16x32_bf16 v[36:39], v[52:55], v[110:113], v[36:39]
	ds_read_b64 v[48:49], v73 offset:37248
	ds_read_b64 v[50:51], v73 offset:37280
	s_waitcnt lgkmcnt(12)
	v_mfma_f32_16x16x32_bf16 v[40:43], v[56:59], v[110:113], v[40:43]
	ds_read_b64 v[52:53], v73 offset:45696
	ds_read_b64 v[54:55], v73 offset:45728
	s_waitcnt lgkmcnt(12)
	v_mfma_f32_16x16x32_bf16 v[44:47], v[60:63], v[110:113], v[44:47]
	ds_read_b64 v[56:57], v73 offset:54144
	ds_read_b64 v[58:59], v73 offset:54176
	s_waitcnt lgkmcnt(12)
	v_mfma_f32_16x16x32_bf16 v[32:35], v[64:67], v[118:121], v[32:35]
	ds_read_b64 v[60:61], v73 offset:62592
	ds_read_b64 v[62:63], v73 offset:62624
	s_waitcnt lgkmcnt(12)
	v_mfma_f32_16x16x32_bf16 v[36:39], v[68:71], v[118:121], v[36:39]
	ds_read_b64 v[64:65], v73 offset:37312
	ds_read_b64 v[66:67], v73 offset:37344
	s_waitcnt lgkmcnt(12)
	v_mfma_f32_16x16x32_bf16 v[40:43], v[82:85], v[118:121], v[40:43]
	ds_read_b64 v[68:69], v73 offset:45760
	ds_read_b64 v[70:71], v73 offset:45792
	s_waitcnt lgkmcnt(12)
	v_mfma_f32_16x16x32_bf16 v[44:47], v[90:93], v[118:121], v[44:47]
	ds_read_b64 v[82:83], v73 offset:54208
	ds_read_b64 v[84:85], v73 offset:54240
	s_waitcnt lgkmcnt(12)
	v_mfma_f32_16x16x32_bf16 v[32:35], v[48:51], v[126:129], v[32:35]
	ds_read_b64 v[90:91], v73 offset:62656
	ds_read_b64 v[92:93], v73 offset:62688
	s_waitcnt lgkmcnt(12)
	v_mfma_f32_16x16x32_bf16 v[36:39], v[52:55], v[126:129], v[36:39]
	s_waitcnt lgkmcnt(10)
	v_mfma_f32_16x16x32_bf16 v[40:43], v[56:59], v[126:129], v[40:43]
	s_waitcnt lgkmcnt(8)
	v_mfma_f32_16x16x32_bf16 v[44:47], v[60:63], v[126:129], v[44:47]
	s_waitcnt lgkmcnt(6)
	v_mfma_f32_16x16x32_bf16 v[32:35], v[64:67], v[134:137], v[32:35]
	s_waitcnt lgkmcnt(4)
	v_mfma_f32_16x16x32_bf16 v[36:39], v[68:71], v[134:137], v[36:39]
	s_waitcnt lgkmcnt(2)
	v_mfma_f32_16x16x32_bf16 v[40:43], v[82:85], v[134:137], v[40:43]
	s_waitcnt lgkmcnt(0)
	v_mfma_f32_16x16x32_bf16 v[44:47], v[90:93], v[134:137], v[44:47]
	ds_read_b128 v[48:51], v72 offset:0
	ds_read_b128 v[52:55], v146 offset:0
	ds_read_b128 v[56:59], v72 offset:2048
	ds_read_b128 v[60:63], v146 offset:2048
	ds_read_b128 v[64:67], v72 offset:4096
	ds_read_b128 v[68:71], v146 offset:4096
	s_add_u32 s16, s12, 0x80000
	s_addc_u32 s17, s13, 0
	s_nop 7
	v_pk_mul_f32 v[32:33], v[32:33], v[142:143]
	v_pk_mul_f32 v[34:35], v[34:35], v[142:143]
	v_pk_mul_f32 v[36:37], v[36:37], v[142:143]
	v_pk_mul_f32 v[38:39], v[38:39], v[142:143]
	v_pk_mul_f32 v[40:41], v[40:41], v[142:143]
	v_pk_mul_f32 v[42:43], v[42:43], v[142:143]
	v_pk_mul_f32 v[44:45], v[44:45], v[142:143]
	v_pk_mul_f32 v[46:47], v[46:47], v[142:143]
	v_cvt_pk_bf16_f32 v32, v32, v33
	v_cvt_pk_bf16_f32 v33, v34, v35
	v_cvt_pk_bf16_f32 v36, v36, v37
	v_cvt_pk_bf16_f32 v37, v38, v39
	v_cvt_pk_bf16_f32 v40, v40, v41
	v_cvt_pk_bf16_f32 v41, v42, v43
	v_cvt_pk_bf16_f32 v44, v44, v45
	v_cvt_pk_bf16_f32 v45, v46, v47
	global_store_dwordx2 v74, v[32:33], s[16:17] offset:0
	global_store_dwordx2 v74, v[36:37], s[16:17] offset:32
	global_store_dwordx2 v74, v[40:41], s[16:17] offset:64
	global_store_dwordx2 v74, v[44:45], s[16:17] offset:96
	ds_read_b128 v[32:35], v72 offset:6144
	ds_read_b128 v[36:39], v146 offset:6144
	ds_read_b128 v[40:43], v72 offset:8192
	s_waitcnt lgkmcnt(8)
	v_mfma_f32_16x16x32_bf16 v[78:81], v[48:51], v[24:27], 0
	ds_read_b128 v[44:47], v146 offset:8192
	s_waitcnt lgkmcnt(8)
	v_mfma_f32_16x16x32_bf16 v[78:81], v[52:55], v[28:31], v[78:81]
	ds_read_b128 v[48:51], v72 offset:10240
	s_waitcnt lgkmcnt(8)
	v_mfma_f32_16x16x32_bf16 v[82:85], v[56:59], v[24:27], 0
	ds_read_b128 v[52:55], v146 offset:10240
	s_waitcnt lgkmcnt(8)
	v_mfma_f32_16x16x32_bf16 v[82:85], v[60:63], v[28:31], v[82:85]
	ds_read_b128 v[56:59], v72 offset:12288
	s_waitcnt lgkmcnt(8)
	v_mfma_f32_16x16x32_bf16 v[86:89], v[64:67], v[24:27], 0
	ds_read_b128 v[60:63], v146 offset:12288
	s_waitcnt lgkmcnt(8)
	v_mfma_f32_16x16x32_bf16 v[86:89], v[68:71], v[28:31], v[86:89]
	ds_read_b128 v[64:67], v72 offset:14336
	s_waitcnt lgkmcnt(8)
	v_mfma_f32_16x16x32_bf16 v[90:93], v[32:35], v[24:27], 0
	ds_read_b128 v[68:71], v146 offset:14336
	s_waitcnt lgkmcnt(8)
	v_mfma_f32_16x16x32_bf16 v[90:93], v[36:39], v[28:31], v[90:93]
	ds_read_b128 v[32:35], v72 offset:16384
	s_waitcnt lgkmcnt(8)
	v_mfma_f32_16x16x32_bf16 v[94:97], v[40:43], v[24:27], 0
	ds_read_b128 v[36:39], v146 offset:16384
	s_waitcnt lgkmcnt(8)
	v_mfma_f32_16x16x32_bf16 v[94:97], v[44:47], v[28:31], v[94:97]
	ds_read_b128 v[40:43], v72 offset:18432
	s_waitcnt lgkmcnt(8)
	v_mfma_f32_16x16x32_bf16 v[98:101], v[48:51], v[24:27], 0
	ds_read_b128 v[44:47], v146 offset:18432
	s_waitcnt lgkmcnt(8)
	v_mfma_f32_16x16x32_bf16 v[98:101], v[52:55], v[28:31], v[98:101]
	ds_read_b128 v[48:51], v72 offset:20480
	s_waitcnt lgkmcnt(8)
	v_mfma_f32_16x16x32_bf16 v[102:105], v[56:59], v[24:27], 0
	ds_read_b128 v[52:55], v146 offset:20480
	s_waitcnt lgkmcnt(8)
	v_mfma_f32_16x16x32_bf16 v[102:105], v[60:63], v[28:31], v[102:105]
	ds_read_b128 v[56:59], v72 offset:22528
	s_waitcnt lgkmcnt(8)
	v_mfma_f32_16x16x32_bf16 v[106:109], v[64:67], v[24:27], 0
	ds_read_b128 v[60:63], v146 offset:22528
	s_waitcnt lgkmcnt(8)
	v_mfma_f32_16x16x32_bf16 v[106:109], v[68:71], v[28:31], v[106:109]
	ds_read_b128 v[64:67], v72 offset:24576
	s_waitcnt lgkmcnt(8)
	v_mfma_f32_16x16x32_bf16 v[110:113], v[32:35], v[24:27], 0
	ds_read_b128 v[68:71], v146 offset:24576
	s_waitcnt lgkmcnt(8)
	v_mfma_f32_16x16x32_bf16 v[110:113], v[36:39], v[28:31], v[110:113]
	ds_read_b128 v[32:35], v72 offset:26624
	s_waitcnt lgkmcnt(8)
	v_mfma_f32_16x16x32_bf16 v[114:117], v[40:43], v[24:27], 0
	ds_read_b128 v[36:39], v146 offset:26624
	s_waitcnt lgkmcnt(8)
	v_mfma_f32_16x16x32_bf16 v[114:117], v[44:47], v[28:31], v[114:117]
	ds_read_b128 v[40:43], v72 offset:28672
	s_waitcnt lgkmcnt(8)
	v_mfma_f32_16x16x32_bf16 v[118:121], v[48:51], v[24:27], 0
	ds_read_b128 v[44:47], v146 offset:28672
	s_waitcnt lgkmcnt(8)
	v_mfma_f32_16x16x32_bf16 v[118:121], v[52:55], v[28:31], v[118:121]
	ds_read_b128 v[48:51], v72 offset:30720
	s_waitcnt lgkmcnt(8)
	v_mfma_f32_16x16x32_bf16 v[122:125], v[56:59], v[24:27], 0
	ds_read_b128 v[52:55], v146 offset:30720
	s_waitcnt lgkmcnt(8)
	v_mfma_f32_16x16x32_bf16 v[122:125], v[60:63], v[28:31], v[122:125]
	s_waitcnt lgkmcnt(7)
	v_mfma_f32_16x16x32_bf16 v[126:129], v[64:67], v[24:27], 0
	s_waitcnt lgkmcnt(6)
	v_mfma_f32_16x16x32_bf16 v[126:129], v[68:71], v[28:31], v[126:129]
	s_waitcnt lgkmcnt(5)
	v_mfma_f32_16x16x32_bf16 v[130:133], v[32:35], v[24:27], 0
	s_waitcnt lgkmcnt(4)
	v_mfma_f32_16x16x32_bf16 v[130:133], v[36:39], v[28:31], v[130:133]
	s_waitcnt lgkmcnt(3)
	v_mfma_f32_16x16x32_bf16 v[134:137], v[40:43], v[24:27], 0
	s_waitcnt lgkmcnt(2)
	v_mfma_f32_16x16x32_bf16 v[134:137], v[44:47], v[28:31], v[134:137]
	s_waitcnt lgkmcnt(1)
	v_mfma_f32_16x16x32_bf16 v[138:141], v[48:51], v[24:27], 0
	s_waitcnt lgkmcnt(0)
	v_mfma_f32_16x16x32_bf16 v[138:141], v[52:55], v[28:31], v[138:141]
	ds_read_b64 v[48:49], v73 offset:36864
	ds_read_b64 v[50:51], v73 offset:36896
	ds_read_b64 v[52:53], v73 offset:45312
	ds_read_b64 v[54:55], v73 offset:45344
	ds_read_b64 v[56:57], v73 offset:53760
	ds_read_b64 v[58:59], v73 offset:53792
	ds_read_b64 v[60:61], v73 offset:62208
	ds_read_b64 v[62:63], v73 offset:62240
	ds_read_b64 v[64:65], v73 offset:36928
	ds_read_b64 v[66:67], v73 offset:36960
	ds_read_b64 v[68:69], v73 offset:45376
	ds_read_b64 v[70:71], v73 offset:45408
	v_max3_f32 v36, v78, v79, v80
	v_max3_f32 v36, v36, v81, v82
	v_max3_f32 v36, v36, v83, v84
	v_max3_f32 v36, v36, v85, v86
	v_max3_f32 v36, v36, v87, v88
	v_max3_f32 v36, v36, v89, v90
	v_max3_f32 v36, v36, v91, v92
	v_max3_f32 v36, v36, v93, v94
	v_max3_f32 v36, v36, v95, v96
	v_max3_f32 v36, v36, v97, v98
	v_max3_f32 v36, v36, v99, v100
	v_max3_f32 v36, v36, v101, v102
	v_max3_f32 v36, v36, v103, v104
	v_max3_f32 v36, v36, v105, v106
	v_max3_f32 v36, v36, v107, v108
	v_max3_f32 v36, v36, v109, v110
	v_max3_f32 v36, v36, v111, v112
	v_max3_f32 v36, v36, v113, v114
	v_max3_f32 v36, v36, v115, v116
	v_max3_f32 v36, v36, v117, v118
	v_max3_f32 v36, v36, v119, v120
	v_max3_f32 v36, v36, v121, v122
	v_max3_f32 v36, v36, v123, v124
	v_max3_f32 v36, v36, v125, v126
	v_max3_f32 v36, v36, v127, v128
	v_max3_f32 v36, v36, v129, v130
	v_max3_f32 v36, v36, v131, v132
	v_max3_f32 v36, v36, v133, v134
	v_max3_f32 v36, v36, v135, v136
	v_max3_f32 v36, v36, v137, v138
	v_max3_f32 v36, v36, v139, v140
	v_max_f32_e32 v36, v36, v141
	v_mov_b32_e32 v37, v36
	s_nop 1
	v_permlane16_swap_b32_e32 v36, v37
	v_max_f32_e32 v36, v36, v37
	v_mov_b32_e32 v37, v36
	s_nop 1
	v_permlane32_swap_b32_e32 v36, v37
	v_max_f32_e32 v36, v36, v37
	v_mul_f32_e64 v38, v36, -v144
	v_mov_b32_e32 v40, 0
	v_mov_b32_e32 v41, 0
	v_mov_b32_e32 v39, v38
	v_pk_fma_f32 v[78:79], v[78:79], v[144:145], v[38:39]
	v_pk_fma_f32 v[80:81], v[80:81], v[144:145], v[38:39]
	v_exp_f32_e32 v78, v78
	v_exp_f32_e32 v79, v79
	v_exp_f32_e32 v80, v80
	v_exp_f32_e32 v81, v81
	v_pk_fma_f32 v[82:83], v[82:83], v[144:145], v[38:39]
	v_pk_fma_f32 v[84:85], v[84:85], v[144:145], v[38:39]
	v_exp_f32_e32 v82, v82
	v_exp_f32_e32 v83, v83
	v_exp_f32_e32 v84, v84
	v_exp_f32_e32 v85, v85
	v_pk_add_f32 v[40:41], v[40:41], v[78:79]
	v_pk_add_f32 v[40:41], v[40:41], v[80:81]
	v_pk_fma_f32 v[86:87], v[86:87], v[144:145], v[38:39]
	v_pk_fma_f32 v[88:89], v[88:89], v[144:145], v[38:39]
	v_exp_f32_e32 v86, v86
	v_exp_f32_e32 v87, v87
	v_exp_f32_e32 v88, v88
	v_exp_f32_e32 v89, v89
	v_pk_add_f32 v[40:41], v[40:41], v[82:83]
	v_pk_add_f32 v[40:41], v[40:41], v[84:85]
	v_pk_fma_f32 v[90:91], v[90:91], v[144:145], v[38:39]
	v_pk_fma_f32 v[92:93], v[92:93], v[144:145], v[38:39]
	v_exp_f32_e32 v90, v90
	v_exp_f32_e32 v91, v91
	v_exp_f32_e32 v92, v92
	v_exp_f32_e32 v93, v93
	v_pk_add_f32 v[40:41], v[40:41], v[86:87]
	v_pk_add_f32 v[40:41], v[40:41], v[88:89]
	v_pk_fma_f32 v[94:95], v[94:95], v[144:145], v[38:39]
	v_pk_fma_f32 v[96:97], v[96:97], v[144:145], v[38:39]
	v_exp_f32_e32 v94, v94
	v_exp_f32_e32 v95, v95
	v_exp_f32_e32 v96, v96
	v_exp_f32_e32 v97, v97
	v_pk_add_f32 v[40:41], v[40:41], v[90:91]
	v_pk_add_f32 v[40:41], v[40:41], v[92:93]
	v_pk_fma_f32 v[98:99], v[98:99], v[144:145], v[38:39]
	v_pk_fma_f32 v[100:101], v[100:101], v[144:145], v[38:39]
	v_exp_f32_e32 v98, v98
	v_exp_f32_e32 v99, v99
	v_exp_f32_e32 v100, v100
	v_exp_f32_e32 v101, v101
	v_pk_add_f32 v[40:41], v[40:41], v[94:95]
	v_pk_add_f32 v[40:41], v[40:41], v[96:97]
	v_pk_fma_f32 v[102:103], v[102:103], v[144:145], v[38:39]
	v_pk_fma_f32 v[104:105], v[104:105], v[144:145], v[38:39]
	v_exp_f32_e32 v102, v102
	v_exp_f32_e32 v103, v103
	v_exp_f32_e32 v104, v104
	v_exp_f32_e32 v105, v105
	v_pk_add_f32 v[40:41], v[40:41], v[98:99]
	v_pk_add_f32 v[40:41], v[40:41], v[100:101]
	v_pk_fma_f32 v[106:107], v[106:107], v[144:145], v[38:39]
	v_pk_fma_f32 v[108:109], v[108:109], v[144:145], v[38:39]
	v_exp_f32_e32 v106, v106
	v_exp_f32_e32 v107, v107
	v_exp_f32_e32 v108, v108
	v_exp_f32_e32 v109, v109
	v_pk_add_f32 v[40:41], v[40:41], v[102:103]
	v_pk_add_f32 v[40:41], v[40:41], v[104:105]
	v_pk_fma_f32 v[110:111], v[110:111], v[144:145], v[38:39]
	v_pk_fma_f32 v[112:113], v[112:113], v[144:145], v[38:39]
	v_exp_f32_e32 v110, v110
	v_exp_f32_e32 v111, v111
	v_exp_f32_e32 v112, v112
	v_exp_f32_e32 v113, v113
	v_pk_add_f32 v[40:41], v[40:41], v[106:107]
	v_pk_add_f32 v[40:41], v[40:41], v[108:109]
	v_pk_fma_f32 v[114:115], v[114:115], v[144:145], v[38:39]
	v_pk_fma_f32 v[116:117], v[116:117], v[144:145], v[38:39]
	v_exp_f32_e32 v114, v114
	v_exp_f32_e32 v115, v115
	v_exp_f32_e32 v116, v116
	v_exp_f32_e32 v117, v117
	v_pk_add_f32 v[40:41], v[40:41], v[110:111]
	v_pk_add_f32 v[40:41], v[40:41], v[112:113]
	v_pk_fma_f32 v[118:119], v[118:119], v[144:145], v[38:39]
	v_pk_fma_f32 v[120:121], v[120:121], v[144:145], v[38:39]
	v_exp_f32_e32 v118, v118
	v_exp_f32_e32 v119, v119
	v_exp_f32_e32 v120, v120
	v_exp_f32_e32 v121, v121
	v_pk_add_f32 v[40:41], v[40:41], v[114:115]
	v_pk_add_f32 v[40:41], v[40:41], v[116:117]
	v_pk_fma_f32 v[122:123], v[122:123], v[144:145], v[38:39]
	v_pk_fma_f32 v[124:125], v[124:125], v[144:145], v[38:39]
	v_exp_f32_e32 v122, v122
	v_exp_f32_e32 v123, v123
	v_exp_f32_e32 v124, v124
	v_exp_f32_e32 v125, v125
	v_pk_add_f32 v[40:41], v[40:41], v[118:119]
	v_pk_add_f32 v[40:41], v[40:41], v[120:121]
	v_pk_fma_f32 v[126:127], v[126:127], v[144:145], v[38:39]
	v_pk_fma_f32 v[128:129], v[128:129], v[144:145], v[38:39]
	v_exp_f32_e32 v126, v126
	v_exp_f32_e32 v127, v127
	v_exp_f32_e32 v128, v128
	v_exp_f32_e32 v129, v129
	v_pk_add_f32 v[40:41], v[40:41], v[122:123]
	v_pk_add_f32 v[40:41], v[40:41], v[124:125]
	v_pk_fma_f32 v[130:131], v[130:131], v[144:145], v[38:39]
	v_pk_fma_f32 v[132:133], v[132:133], v[144:145], v[38:39]
	v_exp_f32_e32 v130, v130
	v_exp_f32_e32 v131, v131
	v_exp_f32_e32 v132, v132
	v_exp_f32_e32 v133, v133
	v_pk_add_f32 v[40:41], v[40:41], v[126:127]
	v_pk_add_f32 v[40:41], v[40:41], v[128:129]
	v_pk_fma_f32 v[134:135], v[134:135], v[144:145], v[38:39]
	v_pk_fma_f32 v[136:137], v[136:137], v[144:145], v[38:39]
	v_exp_f32_e32 v134, v134
	v_exp_f32_e32 v135, v135
	v_exp_f32_e32 v136, v136
	v_exp_f32_e32 v137, v137
	v_pk_add_f32 v[40:41], v[40:41], v[130:131]
	v_pk_add_f32 v[40:41], v[40:41], v[132:133]
	v_pk_fma_f32 v[138:139], v[138:139], v[144:145], v[38:39]
	v_pk_fma_f32 v[140:141], v[140:141], v[144:145], v[38:39]
	v_exp_f32_e32 v138, v138
	v_exp_f32_e32 v139, v139
	v_exp_f32_e32 v140, v140
	v_exp_f32_e32 v141, v141
	v_pk_add_f32 v[40:41], v[40:41], v[134:135]
	v_pk_add_f32 v[40:41], v[40:41], v[136:137]
	s_nop 0
	v_pk_add_f32 v[40:41], v[40:41], v[138:139]
	v_pk_add_f32 v[40:41], v[40:41], v[140:141]
	v_add_f32_e32 v36, v40, v41
	v_mov_b32_e32 v37, v36
	s_nop 1
	v_permlane16_swap_b32_e32 v36, v37
	v_add_f32_e32 v36, v36, v37
	v_mov_b32_e32 v37, v36
	s_nop 1
	v_permlane32_swap_b32_e32 v36, v37
	v_add_f32_e32 v36, v36, v37
	v_rcp_f32_e32 v142, v36
	v_cvt_pk_bf16_f32 v78, v78, v79
	v_cvt_pk_bf16_f32 v79, v80, v81
	v_cvt_pk_bf16_f32 v80, v82, v83
	v_cvt_pk_bf16_f32 v81, v84, v85
	v_cvt_pk_bf16_f32 v86, v86, v87
	v_cvt_pk_bf16_f32 v87, v88, v89
	v_cvt_pk_bf16_f32 v88, v90, v91
	v_cvt_pk_bf16_f32 v89, v92, v93
	v_cvt_pk_bf16_f32 v94, v94, v95
	v_cvt_pk_bf16_f32 v95, v96, v97
	v_cvt_pk_bf16_f32 v96, v98, v99
	v_cvt_pk_bf16_f32 v97, v100, v101
	v_cvt_pk_bf16_f32 v102, v102, v103
	v_cvt_pk_bf16_f32 v103, v104, v105
	v_cvt_pk_bf16_f32 v104, v106, v107
	v_cvt_pk_bf16_f32 v105, v108, v109
	v_cvt_pk_bf16_f32 v110, v110, v111
	v_cvt_pk_bf16_f32 v111, v112, v113
	v_cvt_pk_bf16_f32 v112, v114, v115
	v_cvt_pk_bf16_f32 v113, v116, v117
	v_cvt_pk_bf16_f32 v118, v118, v119
	v_cvt_pk_bf16_f32 v119, v120, v121
	v_cvt_pk_bf16_f32 v120, v122, v123
	v_cvt_pk_bf16_f32 v121, v124, v125
	v_cvt_pk_bf16_f32 v126, v126, v127
	v_cvt_pk_bf16_f32 v127, v128, v129
	v_cvt_pk_bf16_f32 v128, v130, v131
	v_cvt_pk_bf16_f32 v129, v132, v133
	v_cvt_pk_bf16_f32 v134, v134, v135
	v_cvt_pk_bf16_f32 v135, v136, v137
	v_cvt_pk_bf16_f32 v136, v138, v139
	v_cvt_pk_bf16_f32 v137, v140, v141
	v_fma_f32 v143, -v36, v142, 1.0
	v_fma_f32 v142, v143, v142, v142
	v_mov_b32_e32 v143, v142
	ds_read_b64 v[82:83], v73 offset:53824
	ds_read_b64 v[84:85], v73 offset:53856
	s_waitcnt lgkmcnt(12)
	v_mfma_f32_16x16x32_bf16 v[32:35], v[48:51], v[78:81], 0
	ds_read_b64 v[90:91], v73 offset:62272
	ds_read_b64 v[92:93], v73 offset:62304
	s_waitcnt lgkmcnt(12)
	v_mfma_f32_16x16x32_bf16 v[36:39], v[52:55], v[78:81], 0
	ds_read_b64 v[48:49], v73 offset:36992
	ds_read_b64 v[50:51], v73 offset:37024
	s_waitcnt lgkmcnt(12)
	v_mfma_f32_16x16x32_bf16 v[40:43], v[56:59], v[78:81], 0
	ds_read_b64 v[52:53], v73 offset:45440
	ds_read_b64 v[54:55], v73 offset:45472
	s_waitcnt lgkmcnt(12)
	v_mfma_f32_16x16x32_bf16 v[44:47], v[60:63], v[78:81], 0
	ds_read_b64 v[56:57], v73 offset:53888
	ds_read_b64 v[58:59], v73 offset:53920
	s_waitcnt lgkmcnt(12)
	v_mfma_f32_16x16x32_bf16 v[32:35], v[64:67], v[86:89], v[32:35]
	ds_read_b64 v[60:61], v73 offset:62336
	ds_read_b64 v[62:63], v73 offset:62368
	s_waitcnt lgkmcnt(12)
	v_mfma_f32_16x16x32_bf16 v[36:39], v[68:71], v[86:89], v[36:39]
	ds_read_b64 v[64:65], v73 offset:37056
	ds_read_b64 v[66:67], v73 offset:37088
	s_waitcnt lgkmcnt(12)
	v_mfma_f32_16x16x32_bf16 v[40:43], v[82:85], v[86:89], v[40:43]
	ds_read_b64 v[68:69], v73 offset:45504
	ds_read_b64 v[70:71], v73 offset:45536
	s_waitcnt lgkmcnt(12)
	v_mfma_f32_16x16x32_bf16 v[44:47], v[90:93], v[86:89], v[44:47]
	ds_read_b64 v[82:83], v73 offset:53952
	ds_read_b64 v[84:85], v73 offset:53984
	s_waitcnt lgkmcnt(12)
	v_mfma_f32_16x16x32_bf16 v[32:35], v[48:51], v[94:97], v[32:35]
	ds_read_b64 v[90:91], v73 offset:62400
	ds_read_b64 v[92:93], v73 offset:62432
	s_waitcnt lgkmcnt(12)
	v_mfma_f32_16x16x32_bf16 v[36:39], v[52:55], v[94:97], v[36:39]
	ds_read_b64 v[48:49], v73 offset:37120
	ds_read_b64 v[50:51], v73 offset:37152
	s_waitcnt lgkmcnt(12)
	v_mfma_f32_16x16x32_bf16 v[40:43], v[56:59], v[94:97], v[40:43]
	ds_read_b64 v[52:53], v73 offset:45568
	ds_read_b64 v[54:55], v73 offset:45600
	s_waitcnt lgkmcnt(12)
	v_mfma_f32_16x16x32_bf16 v[44:47], v[60:63], v[94:97], v[44:47]
	ds_read_b64 v[56:57], v73 offset:54016
	ds_read_b64 v[58:59], v73 offset:54048
	s_waitcnt lgkmcnt(12)
	v_mfma_f32_16x16x32_bf16 v[32:35], v[64:67], v[102:105], v[32:35]
	ds_read_b64 v[60:61], v73 offset:62464
	ds_read_b64 v[62:63], v73 offset:62496
	s_waitcnt lgkmcnt(12)
	v_mfma_f32_16x16x32_bf16 v[36:39], v[68:71], v[102:105], v[36:39]
	ds_read_b64 v[64:65], v73 offset:37184
	ds_read_b64 v[66:67], v73 offset:37216
	s_waitcnt lgkmcnt(12)
	v_mfma_f32_16x16x32_bf16 v[40:43], v[82:85], v[102:105], v[40:43]
	ds_read_b64 v[68:69], v73 offset:45632
	ds_read_b64 v[70:71], v73 offset:45664
	s_waitcnt lgkmcnt(12)
	v_mfma_f32_16x16x32_bf16 v[44:47], v[90:93], v[102:105], v[44:47]
	ds_read_b64 v[82:83], v73 offset:54080
	ds_read_b64 v[84:85], v73 offset:54112
	s_waitcnt lgkmcnt(12)
	v_mfma_f32_16x16x32_bf16 v[32:35], v[48:51], v[110:113], v[32:35]
	ds_read_b64 v[90:91], v73 offset:62528
	ds_read_b64 v[92:93], v73 offset:62560
	s_waitcnt lgkmcnt(12)
	v_mfma_f32_16x16x32_bf16 v[36:39], v[52:55], v[110:113], v[36:39]
	ds_read_b64 v[48:49], v73 offset:37248
	ds_read_b64 v[50:51], v73 offset:37280
	s_waitcnt lgkmcnt(12)
	v_mfma_f32_16x16x32_bf16 v[40:43], v[56:59], v[110:113], v[40:43]
	ds_read_b64 v[52:53], v73 offset:45696
	ds_read_b64 v[54:55], v73 offset:45728
	s_waitcnt lgkmcnt(12)
	v_mfma_f32_16x16x32_bf16 v[44:47], v[60:63], v[110:113], v[44:47]
	ds_read_b64 v[56:57], v73 offset:54144
	ds_read_b64 v[58:59], v73 offset:54176
	s_waitcnt lgkmcnt(12)
	v_mfma_f32_16x16x32_bf16 v[32:35], v[64:67], v[118:121], v[32:35]
	ds_read_b64 v[60:61], v73 offset:62592
	ds_read_b64 v[62:63], v73 offset:62624
	s_waitcnt lgkmcnt(12)
	v_mfma_f32_16x16x32_bf16 v[36:39], v[68:71], v[118:121], v[36:39]
	ds_read_b64 v[64:65], v73 offset:37312
	ds_read_b64 v[66:67], v73 offset:37344
	s_waitcnt lgkmcnt(12)
	v_mfma_f32_16x16x32_bf16 v[40:43], v[82:85], v[118:121], v[40:43]
	ds_read_b64 v[68:69], v73 offset:45760
	ds_read_b64 v[70:71], v73 offset:45792
	s_waitcnt lgkmcnt(12)
	v_mfma_f32_16x16x32_bf16 v[44:47], v[90:93], v[118:121], v[44:47]
	ds_read_b64 v[82:83], v73 offset:54208
	ds_read_b64 v[84:85], v73 offset:54240
	s_waitcnt lgkmcnt(12)
	v_mfma_f32_16x16x32_bf16 v[32:35], v[48:51], v[126:129], v[32:35]
	ds_read_b64 v[90:91], v73 offset:62656
	ds_read_b64 v[92:93], v73 offset:62688
	s_waitcnt lgkmcnt(12)
	v_mfma_f32_16x16x32_bf16 v[36:39], v[52:55], v[126:129], v[36:39]
	s_waitcnt lgkmcnt(10)
	v_mfma_f32_16x16x32_bf16 v[40:43], v[56:59], v[126:129], v[40:43]
	s_waitcnt lgkmcnt(8)
	v_mfma_f32_16x16x32_bf16 v[44:47], v[60:63], v[126:129], v[44:47]
	s_waitcnt lgkmcnt(6)
	v_mfma_f32_16x16x32_bf16 v[32:35], v[64:67], v[134:137], v[32:35]
	s_waitcnt lgkmcnt(4)
	v_mfma_f32_16x16x32_bf16 v[36:39], v[68:71], v[134:137], v[36:39]
	s_waitcnt lgkmcnt(2)
	v_mfma_f32_16x16x32_bf16 v[40:43], v[82:85], v[134:137], v[40:43]
	s_waitcnt lgkmcnt(0)
	v_mfma_f32_16x16x32_bf16 v[44:47], v[90:93], v[134:137], v[44:47]
	s_add_u32 s16, s12, 0x88000
	s_addc_u32 s17, s13, 0
	s_nop 7
	v_pk_mul_f32 v[32:33], v[32:33], v[142:143]
	v_pk_mul_f32 v[34:35], v[34:35], v[142:143]
	v_pk_mul_f32 v[36:37], v[36:37], v[142:143]
	v_pk_mul_f32 v[38:39], v[38:39], v[142:143]
	v_pk_mul_f32 v[40:41], v[40:41], v[142:143]
	v_pk_mul_f32 v[42:43], v[42:43], v[142:143]
	v_pk_mul_f32 v[44:45], v[44:45], v[142:143]
	v_pk_mul_f32 v[46:47], v[46:47], v[142:143]
	v_cvt_pk_bf16_f32 v32, v32, v33
	v_cvt_pk_bf16_f32 v33, v34, v35
	v_cvt_pk_bf16_f32 v36, v36, v37
	v_cvt_pk_bf16_f32 v37, v38, v39
	v_cvt_pk_bf16_f32 v40, v40, v41
	v_cvt_pk_bf16_f32 v41, v42, v43
	v_cvt_pk_bf16_f32 v44, v44, v45
	v_cvt_pk_bf16_f32 v45, v46, v47
	global_store_dwordx2 v74, v[32:33], s[16:17] offset:0
	global_store_dwordx2 v74, v[36:37], s[16:17] offset:32
	global_store_dwordx2 v74, v[40:41], s[16:17] offset:64
	global_store_dwordx2 v74, v[44:45], s[16:17] offset:96
	s_setprio 0
	s_cmp_eq_u32 m0, 0x1234
	s_cbranch_scc1 .Latt_late_ret
	s_branch .LBB0_270
